# v30 code with phase-start and post-patch labels pinned to the baseline's byte offset mod 256 (placement control)
# speedup vs baseline: 1.0026x; 1.0026x over previous
; #define LAS __attribute__((address_space(3)))
; #define SEAM(k) do { if (IN(k) && IN((k) + 1)) xcd_barrier(bar); } while (0)
; template <bool FIRST>
; __device__ __forceinline__ void phase_norm(const Args& a, LAS unsigned char* lds, int tid, int wave, int lane, int vcu, int G) {
;     unsigned char* ws = a.ws;
;     const float* mod = (const float*)(ws + WS_MOD);
;     const float* gvec = a.in[FIRST ? 11 : 16];
;     bf16* H = (bf16*)(ws + WS_H);
;     LAS float* WG = (LAS float*)lds;
;     if (FIRST) {
;         for (int i = tid; i < DM * 8; i += NTHREADS) WG[(i & 7) * DM + (i >> 3)] = a.in[12][(size_t)(i >> 3) * 3592 + 3584 + (i & 7)];
;         __syncthreads();
; __global__ void __launch_bounds__(NTHREADS, 2) hymba_fwd(Args args) {
;     ...
;     if (IN(0)) for (int rep_ = 0; rep_ < NREP(0); ++rep_) { if (rep_) xcd_barrier(bar); phase0(args, lds, tid, wave, lane, vcu, G, rep_ ? PROBE_P0MASK : 15); } SEAM(0);
;     if (IN(1)) for (int rep_ = 0; rep_ < NREP(1); ++rep_) { if (rep_) xcd_barrier(bar); phase_norm<true>(args, lds, tid, wave, lane, vcu, G); } SEAM(1);
.LBB0_127:
	s_or_b64 exec, exec, s[4:5]
	s_waitcnt lgkmcnt(0)
	s_barrier
	s_branch .Lpin_0
	.p2align 8
	s_nop 0
	s_nop 0
	s_nop 0
	s_nop 0
	s_nop 0
	s_nop 0
	s_nop 0
	s_nop 0
	s_nop 0
	s_nop 0
	s_nop 0
	s_nop 0
	s_nop 0
	s_nop 0
	s_nop 0
	s_nop 0
	s_nop 0
	s_nop 0
	s_nop 0
	s_nop 0
	s_nop 0
	s_nop 0
	s_nop 0
	s_nop 0
	s_nop 0
	s_nop 0
	s_nop 0
	s_nop 0
	s_nop 0
	s_nop 0
	s_nop 0
	s_nop 0
	s_nop 0
	s_nop 0
	s_nop 0
	s_nop 0
	s_nop 0
	s_nop 0
.Lpin_0:
.LBB0_128:
	s_cmp_lt_i32 s86, 2
	s_cselect_b64 s[24:25], -1, 0
	s_and_b64 s[2:3], s[24:25], s[2:3]
	s_andn2_b64 vcc, exec, s[2:3]
	v_and_b32_e32 v184, 7, v0
	s_cbranch_vccnz .LBB0_162
	v_lshlrev_b32_e32 v3, 12, v184
	v_or_b32_e32 v1, 0x200, v0
	v_add_u32_e32 v6, 0, v3
	v_or_b32_e32 v2, 0xe00, v184
	v_mov_b32_e32 v7, 8
	s_mov_b64 s[2:3], 0
	s_movk_i32 s4, 0xe08
	v_mov_b32_e32 v8, 0
	s_waitcnt vmcnt(0)
	v_mov_b64_e32 v[4:5], v[0:1]

;     __host__ __device__ bool next(int i, Unit& u) const { if (!S.next(i >> 1, u)) return false; u.half = i & 1; return true; }
;     __host__ __device__ bool next(int i, Unit& u) const {
;         const long L = (long)i * G + c; if (L >= nwg) return false;
;         int wgid = (int)L; { const int q = nwg / NXCD, r = nwg % NXCD, xcd = wgid % NXCD, off = wgid / NXCD; wgid = (xcd < r ? xcd * (q + 1) : r * (q + 1) + (xcd - r) * q) + off; }
;         const int nig = WGM * nN, gid = wgid / nig, fm = gid * WGM, gsz = (nM - fm) < WGM ? (nM - fm) : WGM;
;         u.pm = fm + ((wgid % nig) % gsz); u.pn = (wgid % nig) / gsz; return true;
.LBB0_211:
	s_or_b64 exec, exec, s[2:3]
	s_waitcnt lgkmcnt(0)
	s_barrier
	s_branch .Lpin_1
	.p2align 8
	s_nop 0
	s_nop 0
	s_nop 0
	s_nop 0
	s_nop 0
	s_nop 0
	s_nop 0
.Lpin_1:
.LBB0_212:
	s_cmp_lt_i32 s86, 3
	s_cselect_b64 s[6:7], -1, 0
	s_and_b64 s[0:1], s[6:7], s[0:1]
	s_andn2_b64 vcc, exec, s[0:1]
	s_cbranch_vccnz .LBB0_568
	v_readlane_b32 s2, v253, 4
	s_cmpk_lt_i32 s2, 0x2a8
	s_cselect_b64 s[0:1], -1, 0
	s_cmpk_gt_i32 s2, 0x2a7
	v_readfirstlane_b32 s26, v0
	s_cbranch_scc1 .LBB0_215
	v_readlane_b32 s4, v253, 4
	s_ashr_i32 s2, s4, 31
	s_lshr_b32 s2, s2, 29
	s_add_i32 s2, s4, s2
	s_ashr_i32 s3, s2, 3
	s_and_b32 s2, s2, -8
	s_sub_i32 s2, s4, s2
	s_cmp_lt_i32 s2, 0
	s_movk_i32 s4, 0x56
	s_cselect_b32 s4, s4, 0x55
	s_mul_i32 s2, s2, s4
	s_add_i32 s2, s2, s3
	s_mul_hi_i32 s3, s2, 0x66666667
	s_lshr_b32 s4, s3, 31
	s_ashr_i32 s3, s3, 5
	s_add_i32 s3, s3, s4
	s_lshl_b32 s4, s3, 3
	s_sub_i32 s5, 0x44, s4
	s_mulk_i32 s3, 0x50
	s_min_u32 s5, s5, 8
	s_sub_i32 s8, s2, s3
	s_sext_i32_i8 s2, s8
	s_waitcnt vmcnt(0)
	v_cvt_f32_ubyte0_e32 v2, s5
	v_cvt_f32_i32_e32 v1, s2
	v_rcp_iflag_f32_e32 v3, v2
	s_ashr_i32 s2, s2, 30
	s_or_b32 s9, s2, 1
	v_mul_f32_e32 v3, v1, v3
	v_trunc_f32_e32 v3, v3
	v_fma_f32 v1, -v3, v2, v1
	v_cvt_i32_f32_e32 v3, v3
	v_cmp_ge_f32_e64 s[2:3], |v1|, v2
	s_and_b64 s[2:3], s[2:3], exec
	s_cselect_b32 s2, s9, 0
	v_readfirstlane_b32 s3, v3
	s_add_i32 s2, s3, s2
	s_sext_i32_i8 s40, s2
	s_mul_i32 s2, s2, s5
	s_sub_i32 s2, s8, s2
	s_sext_i32_i8 s2, s2
	s_add_i32 s2, s4, s2

; #define LAS __attribute__((address_space(3)))
; #define SEAM(k) do { if (IN(k) && IN((k) + 1)) xcd_barrier(bar); } while (0)
; template <int MASK> __device__ __forceinline__ void phase3(const Args& a, LAS unsigned char* lds, int tid, int wave, int lane, int vcu, int G) {
;     unsigned char* ws = a.ws;
;     const bf16* P1 = (const bf16*)(ws + WS_P1); const bf16* PT = (const bf16*)(ws + WS_PT);
;     const float* IG = (const float*)(ws + WS_IG); const float* LF = (const float*)(ws + WS_LF);
;     const int i16 = lane & 15, g = lane >> 4;
;     const int gw = vcu * NWAVES + wave, NGW = G * NWAVES;
;     const bool swap_ = G == 256 && (vcu & 1);
;     for (int s_ = 0; s_ < 2; ++s_) {
;     const bool do_iv = (s_ == 0) != swap_;
;     if ((MASK & 1) && do_iv) {
;         bf16* ATT = (bf16*)(ws + WS_ATT);
;         LAS float* ST = (LAS float*)lds;
; __global__ void __launch_bounds__(NTHREADS, 2) hymba_fwd(Args args) {
;     ...
;     if (IN(3)) for (int rep_ = 0; rep_ < NREP(3); ++rep_) { if (rep_) xcd_barrier(bar); if (rep_ == 0) phase3<15>(args, lds, tid, wave, lane, vcu, G); else phase3<PROBE_P3MASK>(args, lds, tid, wave, lane, vcu, G); } SEAM(3);
.LBB0_617:
	s_or_b64 exec, exec, s[2:3]
	s_waitcnt lgkmcnt(0)
	s_barrier
	s_branch .Lpin_2
	.p2align 8
	s_nop 0
	s_nop 0
	s_nop 0
	s_nop 0
	s_nop 0
	s_nop 0
	s_nop 0
	s_nop 0
	s_nop 0
	s_nop 0
	s_nop 0
	s_nop 0
	s_nop 0
	s_nop 0
	s_nop 0
	s_nop 0
	s_nop 0
	s_nop 0
	s_nop 0
	s_nop 0
	s_nop 0
	s_nop 0
	s_nop 0
	s_nop 0
	s_nop 0
	s_nop 0
	s_nop 0
	s_nop 0
	s_nop 0
	s_nop 0
	s_nop 0
	s_nop 0
	s_nop 0
	s_nop 0
	s_nop 0
	s_nop 0
	s_nop 0
	s_nop 0
	s_nop 0
	s_nop 0
	s_nop 0
	s_nop 0
	s_nop 0
	s_nop 0
	s_nop 0
	s_nop 0
.Lpin_2:
.LBB0_618:
	s_cmp_lt_i32 s86, 4
	s_cselect_b64 s[2:3], -1, 0
	s_and_b64 s[0:1], s[2:3], s[0:1]
	s_andn2_b64 vcc, exec, s[0:1]
	v_cmp_eq_u32_e64 s[0:1], 0, v166
	v_lshrrev_b32_e32 v168, 2, v0
	v_writelane_b32 v253, s93, 49
	s_cbranch_vccnz .LBB0_914
	s_add_u32 s56, s84, 0x7d00000
	s_addc_u32 s57, s85, 0
	s_add_u32 s58, s84, 0xd200000
	s_addc_u32 s59, s85, 0
	v_writelane_b32 v253, s2, 50
	s_add_u32 s74, s84, 0x700000
	s_addc_u32 s75, s85, 0
	v_writelane_b32 v253, s3, 51
	s_add_u32 s78, s84, 0x800000
	v_readlane_b32 s40, v253, 5
	s_addc_u32 s79, s85, 0
	s_lshl_b32 s2, s40, 3
	v_readlane_b32 s38, v253, 27
	v_readlane_b32 s66, v253, 2
	s_add_i32 s24, s2, s38
	s_lshl_b32 s94, s66, 3
	s_cmpk_eq_i32 s66, 0x100
	s_cselect_b64 s[2:3], -1, 0
	s_bitcmp1_b32 s40, 0
	s_cselect_b64 s[4:5], -1, 0
	s_and_b64 s[28:29], s[2:3], s[4:5]
	s_add_u32 s2, s84, 0x12500000
	v_readlane_b32 s41, v253, 6
	v_readlane_b32 s39, v253, 28
	v_readlane_b32 s67, v253, 3
	v_writelane_b32 v253, s2, 52
	s_addc_u32 s2, s85, 0
	s_cmpk_lt_i32 s40, 0x100
	v_writelane_b32 v253, s2, 54
	s_cselect_b64 s[2:3], -1, 0
	v_writelane_b32 v253, s2, 55
	s_bfe_u32 s35, s93, 0x20006
	s_lshr_b32 s26, s93, 8
	v_writelane_b32 v253, s3, 56
	s_mov_b32 s88, s93
	s_mul_i32 s93, s38, 17
	s_mul_i32 s2, s38, 0xffffffef
	s_add_i32 s33, s93, 0xffffff80
	s_add_i32 s34, s2, 0x80
	s_cmpk_lt_u32 s88, 0x100
	s_cselect_b64 s[4:5], -1, 0
	v_writelane_b32 v253, s4, 57
	s_mul_i32 s3, s38, 0x3c00
	s_mov_b64 s[80:81], s[84:85]
	v_writelane_b32 v253, s5, 58
	s_add_i32 s5, s3, 0
	s_add_u32 s3, s84, 0x23700000
	v_writelane_b32 v253, s3, 59
	s_addc_u32 s3, s85, 0
	s_add_u32 s6, s84, 0x900000
	v_writelane_b32 v253, s3, 61
	s_addc_u32 s7, s85, 0
	v_writelane_b32 v253, s6, 63
	s_mov_b64 s[82:83], s[86:87]
	v_and_b32_e32 v1, 15, v0
	v_writelane_b32 v254, s7, 0
	s_add_u32 s6, s84, 0xa00000
	s_addc_u32 s7, s85, 0
	v_writelane_b32 v254, s6, 1
	s_add_u32 s3, s84, 0xb00000
	v_mov_b32_e32 v95, 0
	v_writelane_b32 v254, s7, 2
	v_writelane_b32 v254, s3, 3
	s_addc_u32 s3, s85, 0
	v_writelane_b32 v254, s3, 4
	s_add_u32 s3, s84, 0x1e200000
	v_writelane_b32 v254, s3, 5
	s_addc_u32 s3, s85, 0
	s_cmpk_lt_i32 s40, 0x200
	v_writelane_b32 v254, s3, 7
	s_cselect_b64 s[6:7], -1, 0
	v_writelane_b32 v254, s6, 9
	s_cmp_lt_u32 s88, 64
	s_cselect_b64 s[82:83], -1, 0
	v_writelane_b32 v254, s7, 10
	v_cmp_gt_u32_e64 s[6:7], 16, v166
	v_lshlrev_b32_e32 v94, 3, v1
	v_lshl_add_u64 v[96:97], s[56:57], 0, v[94:95]
	v_writelane_b32 v254, s6, 11
	v_lshlrev_b32_e32 v94, 2, v166
	s_waitcnt vmcnt(0)
	v_lshl_add_u64 v[2:3], s[80:81], 0, v[94:95]
	v_writelane_b32 v254, s7, 12
	s_and_b64 s[6:7], s[82:83], s[6:7]
	v_writelane_b32 v254, s6, 13
	v_readlane_b32 s8, v253, 33
	v_readlane_b32 s22, v253, 47
	v_writelane_b32 v254, s7, 14
	s_mov_b64 s[6:7], 0x20200000
	v_lshl_add_u64 v[98:99], v[2:3], 0, s[6:7]
	s_add_u32 s6, s80, 0x23800000
	s_addc_u32 s7, s81, 0
	v_writelane_b32 v254, s6, 15
	v_readlane_b32 s23, v253, 48
	v_and_b32_e32 v107, 3, v0
	v_writelane_b32 v254, s7, 16
	v_subrev_co_u32_e64 v6, s[6:7], 64, v0
	v_lshlrev_b32_e32 v4, 1, v168
	s_nop 0
	v_writelane_b32 v254, s6, 17
	v_mov_b32_e32 v5, v95
	v_readlane_b32 s16, v253, 41
	v_writelane_b32 v254, s7, 18
	s_xor_b64 s[6:7], s[6:7], -1
	s_add_u32 s68, s80, 0xe300000
	v_writelane_b32 v254, s6, 19
	v_readlane_b32 s17, v253, 42
	v_readlane_b32 s18, v253, 43
	v_readlane_b32 s19, v253, 44
	v_readlane_b32 s20, v253, 45
	v_readlane_b32 s21, v253, 46
	s_mov_b64 s[50:51], s[22:23]
	s_addc_u32 s4, s81, 0
	v_writelane_b32 v254, s7, 20
	v_lshlrev_b32_e32 v2, 7, v107
	v_lshl_add_u64 v[4:5], s[80:81], 0, v[4:5]
	s_mov_b64 s[6:7], 0x22600000
	v_mov_b32_e32 v3, v95
	s_mov_b64 s[48:49], s[20:21]
	s_add_u32 s37, s80, 0x10500000
	v_lshl_add_u64 v[100:101], v[4:5], 0, s[6:7]
	v_lshl_add_u64 v[4:5], s[50:51], 0, v[2:3]
	s_mov_b64 s[6:7], 0x5040810
	v_lshrrev_b32_e32 v13, 4, v0
	s_addc_u32 s48, s81, 0
	v_lshlrev_b32_e32 v7, 4, v1
	v_lshl_add_u64 v[102:103], v[4:5], 0, s[6:7]
	v_mul_u32_u24_e32 v4, 0x1400, v13
	s_add_u32 s49, s80, 0x11500000
	v_mul_hi_u32_u24_e32 v5, 0x1400, v13
	v_or_b32_e32 v4, v4, v7
	s_addc_u32 s54, s81, 0
	v_lshl_add_u64 v[4:5], s[80:81], 0, v[4:5]
	s_mov_b64 s[6:7], 0x7d01000
	s_cmpk_lt_i32 s24, 0x2000
	v_lshl_add_u64 v[104:105], v[4:5], 0, s[6:7]
	v_writelane_b32 v254, s24, 21
	s_cselect_b64 s[6:7], -1, 0
	v_writelane_b32 v254, s6, 23
	s_cmp_eq_u32 s38, 1
	s_mov_b64 s[44:45], s[16:17]
	v_writelane_b32 v254, s7, 24
	s_cselect_b64 s[6:7], -1, 0
	s_cmp_eq_u32 s38, 2
	s_cselect_b64 s[60:61], -1, 0
	s_cmp_eq_u32 s38, 3
	s_cselect_b64 s[62:63], -1, 0
	s_cmp_eq_u32 s38, 4
	s_cselect_b64 s[64:65], -1, 0
	s_cmp_eq_u32 s38, 5
	s_cselect_b64 s[96:97], -1, 0
	s_cmp_eq_u32 s38, 6
	s_cselect_b64 s[42:43], -1, 0
	s_cmp_eq_u32 s38, 7
	s_cselect_b64 s[44:45], -1, 0
	s_cmp_eq_u32 s35, 1
	s_cselect_b64 s[84:85], -1, 0
	s_cmp_eq_u32 s35, 2
	s_mov_b32 s52, s40
	s_cselect_b64 s[40:41], -1, 0
	s_cmp_eq_u32 s35, 3
	s_cselect_b64 s[24:25], -1, 0
	s_and_b32 s2, s2, 3
	s_mov_b64 s[46:47], s[18:19]
	s_cmp_eq_u32 s2, 0
	s_mul_i32 s2, s35, 0x3c00
	s_mul_i32 s3, s38, 0x600
	s_cselect_b64 s[76:77], -1, 0
	s_add_i32 s2, s2, 0
; #define LAS __attribute__((address_space(3)))
; __device__ __forceinline__ float bf_lo(unsigned w) { return __uint_as_float(w << 16); }
; __device__ __forceinline__ float bf_hi(unsigned w) { return __uint_as_float(w & 0xffff0000u); }
; template <int MASK> __device__ __forceinline__ void phase3(const Args& a, LAS unsigned char* lds, int tid, int wave, int lane, int vcu, int G) {
;     ...
;         bf16* ATT = (bf16*)(ws + WS_ATT);
;         LAS float* ST = (LAS float*)lds;
;         struct SState { float m, l; f32x4 o; };
;     ...
;         for (int u = vcu; u < 256; u += G) {
;             const int b = u >> 1, h = (u & 1) * 4 + g;
;             const float* ck = a.in[2] + ((size_t)b * 2048 + 2048) * 512 + h * 64 + 4 * i16;
;             const float* cv = a.in[3] + ((size_t)b * 2048 + 2048) * 512 + h * 64 + 4 * i16;
;             const float* kn = a.out + O_KS + (size_t)b * 8 * 512 + h * 64 + 4 * i16;
;             const float* vn = a.out + O_VS + (size_t)b * 8 * 512 + h * 64 + 4 * i16;
;             f32x4 q[8];
; #pragma unroll
;             for (int t = 0; t < 8; ++t) { const u32x2 qw = *(const u32x2*)(P1 + (size_t)(NP + b * 8 + t) * P1W + C_AQ + h * 64 + 4 * i16); q[t] = (f32x4){bf_lo(qw.x), bf_hi(qw.x), bf_lo(qw.y), bf_hi(qw.y)}; }
;             f32x4 qown = q[0];
; #pragma unroll
;             for (int t = 1; t < 8; ++t) if (wave == t) qown = q[t];
;             const int r4 = wave & 3;
;             SState sF, sM0, sM1, sN[8];
;             sF.m = -1e30f; sF.l = 0.f; sF.o = (f32x4){0.f, 0.f, 0.f, 0.f}; sM0 = sF; sM1 = sF;
;     ...
;                 LAS float* mine = ST + (size_t)wave * (10 * 384) + lane * 6;
;     ...
;                 SA_PUT(0, sM0); SA_PUT(1, sM1);
; #pragma unroll
;                 for (int t = 0; t < 8; ++t) SA_PUT(2 + t, sN[t]);
;             }
;             __syncthreads();
;             {
;                 const int t = wave;
;                 SState acc; acc.m = -1e30f; acc.l = 0.f; acc.o = (f32x4){0.f, 0.f, 0.f, 0.f};
; #pragma unroll
;                 for (int k = 0; k < 10; ++k) {
;                     const int srcw = k < 8 ? k : (t & 3) + 4 * (k - 8), slot = k < 8 ? 2 + t : (t < 4 ? 0 : 1);
;                     const LAS float* p_ = ST + (size_t)srcw * (10 * 384) + slot * 384 + lane * 6;
	s_add_i32 s27, s3, 0
	s_add_i32 s30, 0, 0x12c00
	s_add_i32 s31, 0, 0x16800
	s_add_i32 s36, 0, 0x1a400
	v_writelane_b32 v254, s28, 25
	s_xor_b64 s[46:47], s[28:29], -1
	v_readlane_b32 s9, v253, 34
	s_add_u32 s8, s50, 0x4c00000
	v_mul_u32_u24_e32 v8, 6, v166
	v_writelane_b32 v254, s29, 26
	s_addc_u32 s9, s51, 0
	v_lshlrev_b32_e32 v8, 2, v8
	s_mov_b32 s53, 0
	v_writelane_b32 v254, s9, 27
	s_add_u32 s9, s50, 0x4e00000
	v_add_u32_e32 v109, s5, v8
	v_lshrrev_b32_e32 v9, 3, v6
	s_movk_i32 s5, 0xfe04
	s_mov_b32 s39, s53
	v_writelane_b32 v254, s9, 29
	s_addc_u32 s9, s51, 0
	v_mul_lo_u32 v14, v9, s5
	v_add_u32_e32 v204, s2, v8
	s_lshl_b32 s2, s52, 13
	s_lshl_b32 s5, s38, 10
	v_writelane_b32 v254, s9, 31
	s_lshl_b64 s[28:29], s[38:39], 11
	s_add_i32 s2, s2, s5
	s_or_b32 s5, s38, -4
	v_or_b32_e32 v4, s28, v7
	v_add_u32_e32 v169, s27, v8
	v_writelane_b32 v254, s2, 33
	s_addk_i32 s5, 0xff7c
	s_lshl_b32 s28, s66, 13
	s_lshl_b32 s39, s52, 2
	s_lshl_b32 s2, s66, 2
	s_mul_i32 s27, s38, 0x8800
	v_writelane_b32 v254, s2, 35
	s_mul_hi_u32 s2, s38, 0x8800
	s_add_u32 s50, s27, 0xfffc0000
	v_add_u32_e32 v6, s30, v8
	v_add_u32_e32 v10, s31, v8
	v_add_u32_e32 v11, s36, v8
	s_addc_u32 s51, s2, -1
	s_mov_b32 s2, s38
	v_readlane_b32 s10, v253, 35
	v_readlane_b32 s11, v253, 36
	v_readlane_b32 s12, v253, 37
	v_readlane_b32 s13, v253, 38
	v_readlane_b32 s14, v253, 39
	v_readlane_b32 s15, v253, 40
	v_add_u32_e32 v205, s3, v6
	v_add_u32_e32 v206, s3, v10
	v_add_u32_e32 v207, s3, v11
	v_writelane_b32 v253, s2, 27
	s_mul_i32 s70, s26, 48
	s_mul_i32 s71, s26, 0xffffff40
	v_writelane_b32 v253, s3, 28
	s_movk_i32 s2, 0x80
	v_cmp_gt_u32_e64 s[26:27], s2, v0
	s_add_i32 s2, 0, 0x3024
	v_writelane_b32 v254, s2, 37
	s_add_i32 s2, 0, 0x302c
	v_writelane_b32 v254, s2, 39
	s_add_i32 s2, 0, 0x3034
	v_writelane_b32 v254, s2, 41
	s_add_i32 s2, 0, 0x301c
	v_writelane_b32 v254, s2, 43
	v_cmp_eq_u32_e64 s[2:3], 0, v1
	v_lshrrev_b32_e32 v17, 3, v0
	v_lshrrev_b32_e32 v208, 4, v166
	v_writelane_b32 v254, s2, 44
	v_mov_b32_e32 v5, s29
	s_mov_b32 s29, s8
	v_writelane_b32 v254, s3, 45
	s_mov_b64 s[2:3], -1
	v_writelane_b32 v254, s2, 46
	v_lshlrev_b32_e32 v6, 3, v208
	v_bfe_u32 v8, v0, 2, 2
	v_writelane_b32 v254, s3, 47
	v_cmp_eq_u32_e64 s[2:3], 0, v184
	v_readlane_b32 s8, v253, 11
	v_or_b32_e32 v11, v6, v8
	v_writelane_b32 v254, s2, 48
	v_lshlrev_b32_e32 v8, 3, v0
	v_lshl_add_u32 v16, v9, 9, 0
	v_writelane_b32 v254, s3, 49
	v_cmp_le_u32_e64 s[2:3], v184, v17
	v_and_b32_e32 v9, 0x1fc, v0
	v_and_b32_e32 v108, 0x7f, v0
	v_writelane_b32 v254, s2, 50
	v_readlane_b32 s16, v253, 19
	v_readlane_b32 s17, v253, 20
	v_writelane_b32 v254, s3, 51
	v_cmp_gt_u32_e64 s[2:3], 2, v166
	v_and_b32_e32 v15, 24, v8
	v_add_u32_e32 v217, 0, v2
	v_writelane_b32 v254, s2, 52
	v_add_u32_e32 v218, 0, v9
	v_mul_u32_u24_e32 v9, 0x110, v11
	v_writelane_b32 v254, s3, 53
	v_cmp_gt_u32_e64 s[2:3], 4, v166
	v_lshl_add_u64 v[120:121], s[16:17], 0, v[2:3]
	v_lshlrev_b32_e32 v2, 1, v108
	v_writelane_b32 v254, s2, 54
	v_add3_u32 v220, 0, v9, v15
	v_lshlrev_b32_e32 v9, 9, v208
	v_lshl_add_u64 v[138:139], s[56:57], 0, v[2:3]
	v_mul_u32_u24_e32 v2, 0x110, v13
	v_writelane_b32 v254, s3, 55
	v_cmp_gt_u32_e64 s[2:3], 8, v166
	v_lshl_or_b32 v9, s38, 11, v9
	v_or_b32_e32 v11, 48, v166
	v_add3_u32 v2, v2, v7, 0
	v_writelane_b32 v254, s2, 56
	v_lshlrev_b32_e32 v10, 2, v0
	v_or_b32_e32 v112, v9, v11
	v_or_b32_e32 v11, 0x70, v166
	v_readlane_b32 s14, v253, 17
	v_readlane_b32 s15, v253, 18
	v_add_u32_e32 v222, 0x400, v2
	v_mbcnt_lo_u32_b32 v2, -1, 0
	v_writelane_b32 v254, s3, 57
	v_cmp_gt_u32_e64 s[2:3], 32, v166
	v_lshlrev_b32_e32 v8, 6, v184
	v_lshl_add_u32 v214, v17, 9, 0
	v_lshl_add_u32 v215, v184, 9, 0
	v_mul_i32_i24_e32 v18, 0xfffffe04, v184
	v_mul_i32_i24_e32 v19, 0xfffffe04, v17
	v_add_u32_e32 v216, 0, v10
	v_mul_u32_u24_e32 v20, 60, v0
	v_lshlrev_b32_e32 v12, 4, v166
	v_or_b32_e32 v110, v9, v1
	v_ashrrev_i32_e32 v115, 31, v9
	v_or_b32_e32 v116, v9, v11
	v_mov_b32_e32 v9, v95
	v_readlane_b32 s10, v253, 13
	v_readlane_b32 s11, v253, 14
	v_readlane_b32 s12, v253, 15
	v_readlane_b32 s13, v253, 16
	v_readlane_b32 s18, v253, 21
	v_readlane_b32 s19, v253, 22
	v_mov_b32_e32 v11, v95
	v_lshl_add_u64 v[142:143], s[14:15], 0, v[4:5]
	s_mov_b32 s15, s28
	v_mbcnt_hi_u32_b32 v231, -1, v2
	v_bfrev_b32_e32 v2, 0.5
	v_writelane_b32 v254, s2, 58
	s_mov_b32 s86, 0xfffc0000
	v_lshlrev_b32_e32 v106, 2, v1
	v_lshlrev_b32_e32 v209, 1, v166
	v_lshl_add_u32 v210, v166, 3, 0
	v_lshl_or_b32 v211, s38, 4, v1
	v_lshl_add_u32 v212, v208, 5, 0
	v_mov_b32_e32 v167, v95
	v_add_u32_e32 v213, v16, v8
	v_or_b32_e32 v219, 0x4000, v17
	v_ashrrev_i32_e32 v111, 31, v110
	v_ashrrev_i32_e32 v113, 31, v112
	v_ashrrev_i32_e32 v117, 31, v116
	s_mov_b32 s11, s37
	s_mov_b32 s10, s4
	v_lshl_add_u64 v[118:119], s[18:19], 0, v[8:9]
	v_lshl_add_u64 v[122:123], s[18:19], 0, v[10:11]
	v_mov_b32_e32 v114, v110
	v_or_b32_e32 v124, 16, v110
	v_mov_b32_e32 v125, v115
	v_or_b32_e32 v126, 32, v110
	v_mov_b32_e32 v127, v115
	v_mov_b32_e32 v128, v112
	v_mov_b32_e32 v129, v115
	v_or_b32_e32 v130, 64, v110
	v_mov_b32_e32 v131, v115
	v_or_b32_e32 v132, 0x50, v110
	v_mov_b32_e32 v133, v115
	v_or_b32_e32 v134, 0x60, v110
	v_mov_b32_e32 v135, v115
	v_mov_b32_e32 v136, v116
	v_mov_b32_e32 v137, v115
	v_or_b32_e32 v221, 0xfffffe00, v0
	v_lshrrev_b32_e32 v223, 7, v0
	v_lshlrev_b32_e32 v224, 6, v208
	v_lshl_add_u64 v[140:141], s[12:13], 0, v[4:5]
	s_mov_b32 s13, s49
	s_mov_b32 s12, s48
	s_mov_b32 s14, s54
	v_lshlrev_b32_e32 v144, 1, v6
	v_add_u32_e32 v225, v16, v14
	v_add_u32_e32 v226, v215, v18
	v_add_u32_e32 v227, v214, v19
	v_lshlrev_b32_e32 v146, 2, v0
	v_mov_b32_e32 v228, 0x7080000
	v_add_u32_e32 v229, v216, v20
	v_lshlrev_b32_e32 v230, 1, v12
	v_lshlrev_b32_e32 v148, 1, v94
	v_mov_b32_e32 v232, 0xff800000
	v_lshl_or_b32 v233, v231, 2, v2
	v_mov_b32_e32 v234, 0x1400
	v_mov_b32_e32 v151, 0xf149f2ca
	v_mov_b32_e32 v235, 1
	s_movk_i32 s16, 0x4000
	s_movk_i32 s17, 0x2000
	s_movk_i32 s95, 0x1400
	s_mov_b32 s80, 0xffff0000
	s_movk_i32 s81, 0x7fff
	s_movk_i32 s18, 0x3000
	v_cmp_eq_u32_e64 s[30:31], 0, v0
	v_writelane_b32 v254, s3, 59
	s_mov_b32 s87, -1
	s_mov_b32 s66, s68
	s_mov_b32 s67, s4
	s_mov_b32 s72, s37
	s_mov_b32 s73, s48
	s_mov_b32 s36, s49
	s_mov_b32 s28, s54
	s_mov_b32 s38, s15
	v_readlane_b32 s9, v253, 12
	v_readlane_b32 s20, v253, 23
	v_readlane_b32 s21, v253, 24
	v_readlane_b32 s22, v253, 25
	v_readlane_b32 s23, v253, 26
	s_branch .LBB0_622

; #define LAS __attribute__((address_space(3)))
; __device__ __forceinline__ void phase4(const Args& a, LAS unsigned char* lds, int tid, int wave, int lane, int vcu, int G) {
;     unsigned char* ws = a.ws;
;     const bf16* P1 = (const bf16*)(ws + WS_P1); const bf16* PT = (const bf16*)(ws + WS_PT);
;     const bf16* VT4 = (const bf16*)(ws + WS_VT4); const bf16* VT16 = (const bf16*)(ws + WS_VT16);
;     bf16* ATT = (bf16*)(ws + WS_ATT);
;     const int i16 = lane & 15, g = lane >> 4;
;     LAS float* O = (LAS float*)lds; LAS float* Mx = O + 256 * 68; LAS float* Ls = Mx + 256;
.LBB0_963:
	s_or_b64 exec, exec, s[2:3]
	s_waitcnt lgkmcnt(0)
	s_barrier
	s_branch .Lpin_3
	.p2align 8
	s_nop 0
	s_nop 0
	s_nop 0
	s_nop 0
	s_nop 0
	s_nop 0
	s_nop 0
	s_nop 0
	s_nop 0
	s_nop 0
	s_nop 0
	s_nop 0
	s_nop 0
	s_nop 0
	s_nop 0
	s_nop 0
	s_nop 0
	s_nop 0
	s_nop 0
	s_nop 0
	s_nop 0
	s_nop 0
	s_nop 0
	s_nop 0
	s_nop 0
	s_nop 0
	s_nop 0
.Lpin_3:
.LBB0_964:
	s_cmp_lt_i32 s86, 5
	s_cselect_b64 s[2:3], -1, 0
	v_writelane_b32 v254, s2, 60
	s_and_b64 s[0:1], s[2:3], s[0:1]
	s_andn2_b64 vcc, exec, s[0:1]
	v_writelane_b32 v254, s3, 61
	s_cbranch_vccnz .LBB0_1010
	v_readlane_b32 s0, v253, 5
	s_cmpk_gt_i32 s0, 0x2ff
	v_readlane_b32 s1, v253, 6
	s_cbranch_scc1 .LBB0_1009
	v_readlane_b32 s12, v253, 29
	v_readlane_b32 s13, v253, 30
	s_add_u32 s94, s12, 0x7d00000
	s_addc_u32 s95, s13, 0
	s_add_u32 s0, s12, 0x12500000
	s_addc_u32 s1, s13, 0
	v_writelane_b32 v254, s0, 54
	v_readlane_b32 s10, v253, 2
	s_waitcnt vmcnt(0)
	v_lshrrev_b32_e32 v2, 1, v166
	v_writelane_b32 v254, s1, 55
	s_add_u32 s0, s12, 0x11500000
	s_addc_u32 s1, s13, 0
	s_cmpk_eq_i32 s10, 0x100
	s_cselect_b64 s[2:3], -1, 0
	v_and_b32_e32 v1, 15, v0
	v_writelane_b32 v254, s2, 56
	v_and_b32_e32 v114, 24, v2
	v_lshlrev_b32_e32 v3, 1, v166
	v_writelane_b32 v254, s3, 57
	s_add_u32 s2, s12, 0xe300000
	v_and_b32_e32 v115, 24, v3
	v_sub_u32_e32 v3, v1, v114
	s_movk_i32 s33, 0x81
	s_addc_u32 s3, s13, 0
	v_readlane_b32 s8, v253, 27
	v_cmp_gt_u32_e64 s[4:5], s33, v3
	v_or_b32_e32 v3, 1, v114
	v_readlane_b32 s14, v253, 31
	v_readlane_b32 s15, v253, 32
	v_readlane_b32 s11, v253, 3
	v_writelane_b32 v254, s2, 58
	v_readlane_b32 s9, v253, 28
	v_writelane_b32 v253, s4, 57
	v_sub_u32_e32 v4, v1, v3
	v_writelane_b32 v254, s3, 59
	v_writelane_b32 v253, s5, 58
	v_cmp_gt_u32_e64 s[4:5], s33, v4
	v_or_b32_e32 v150, 2, v114
	v_sub_u32_e32 v4, v1, v150
	v_writelane_b32 v254, s4, 5
	v_or_b32_e32 v151, 3, v114
	v_or_b32_e32 v152, 4, v114
	v_writelane_b32 v254, s5, 6
	v_cmp_gt_u32_e64 s[4:5], s33, v4
	v_sub_u32_e32 v4, v1, v151
	v_or_b32_e32 v153, 5, v114
	v_writelane_b32 v254, s4, 7
	v_or_b32_e32 v154, 6, v114
	v_or_b32_e32 v155, 7, v2
	v_writelane_b32 v254, s5, 8
	v_cmp_gt_u32_e64 s[4:5], s33, v4
	v_sub_u32_e32 v4, v1, v152
	v_sub_u32_e32 v2, v1, v155
	v_writelane_b32 v254, s4, 13
	v_or_b32_e32 v147, 16, v1
	s_lshl_b32 s2, s8, 5
	v_writelane_b32 v254, s5, 14
	v_cmp_gt_u32_e64 s[4:5], s33, v4
	v_sub_u32_e32 v4, v1, v153
	s_add_i32 s3, 0, 0x11000
	v_writelane_b32 v254, s4, 17
	v_add_u32_e32 v164, 0xffffff70, v114
	v_add_u32_e32 v165, 0xffffff71, v114
	v_writelane_b32 v254, s5, 18
	v_cmp_gt_u32_e64 s[4:5], s33, v4
	v_sub_u32_e32 v4, v1, v154
	v_add_u32_e32 v167, 0xffffff72, v114
	v_writelane_b32 v254, s4, 19
	v_add_u32_e32 v169, 0xffffff73, v114
	v_add_u32_e32 v170, 0xffffff74, v114
	v_writelane_b32 v254, s5, 20
	v_cmp_gt_u32_e64 s[4:5], s33, v4
	v_add_u32_e32 v171, 0xffffff75, v114
	v_add_u32_e32 v172, 0xffffff76, v114
	v_writelane_b32 v254, s4, 27
	v_add_u32_e32 v173, 0xffffff77, v114
	v_add_u32_e32 v197, -16, v114
	v_writelane_b32 v254, s5, 28
	v_cmp_gt_u32_e64 s[4:5], s33, v2
	v_sub_u32_e32 v2, v147, v114
	v_add_u32_e32 v198, -15, v114
	v_writelane_b32 v254, s4, 29
	v_add_u32_e32 v199, -14, v114
	v_add_u32_e32 v200, -13, v114
	v_writelane_b32 v254, s5, 30
	v_cmp_gt_u32_e64 s[4:5], s33, v2
	v_sub_u32_e32 v2, v147, v3
	v_add_u32_e32 v201, -12, v114
	v_writelane_b32 v254, s4, 31
	v_add_u32_e32 v202, -11, v114
	v_add_u32_e32 v203, -10, v114
	v_writelane_b32 v254, s5, 32
	v_cmp_gt_u32_e64 s[4:5], s33, v2
	v_sub_u32_e32 v2, v147, v150
	v_add_u32_e32 v204, -9, v114
	v_writelane_b32 v254, s4, 35
	v_and_b32_e32 v5, 1, v0
	v_lshrrev_b32_e32 v213, 7, v0
	v_writelane_b32 v254, s5, 36
	v_cmp_gt_u32_e64 s[4:5], s33, v2
	v_sub_u32_e32 v2, v147, v151
	v_lshlrev_b32_e32 v4, 4, v1
	v_writelane_b32 v254, s4, 44
	v_lshrrev_b32_e32 v205, 1, v0
	v_mul_u32_u24_e32 v8, 0x110, v205
	v_writelane_b32 v254, s5, 45
	v_cmp_gt_u32_e64 s[4:5], s33, v2
	v_sub_u32_e32 v2, v147, v152
	v_lshlrev_b32_e32 v9, 7, v5
	v_writelane_b32 v254, s4, 48
	v_mov_b32_e32 v117, 0
	v_lshlrev_b32_e32 v116, 1, v114
	v_writelane_b32 v254, s5, 49
	v_cmp_gt_u32_e64 s[4:5], s33, v2
	v_sub_u32_e32 v2, v147, v153
	v_add3_u32 v207, 0, v8, v9
	v_writelane_b32 v253, s4, 59
	v_and_b32_e32 v8, 0x7f, v0
	v_lshl_add_u64 v[118:119], s[94:95], 0, v[116:117]
	v_writelane_b32 v253, s5, 60
	v_cmp_gt_u32_e64 s[4:5], s33, v2
	v_sub_u32_e32 v2, v147, v154
	v_lshlrev_b32_e32 v116, 22, v213
	v_writelane_b32 v253, s4, 61
	v_cmp_gt_u32_e64 s[34:35], 16, v166
	v_lshlrev_b32_e32 v122, 2, v0
	v_writelane_b32 v253, s5, 62
	v_cmp_gt_u32_e64 s[4:5], s33, v2
	v_sub_u32_e32 v2, v147, v155
	v_mov_b32_e32 v123, v117
	v_writelane_b32 v253, s4, 63
	v_and_b32_e32 v121, 3, v0
	v_readlane_b32 s9, v253, 49
	v_writelane_b32 v254, s5, 0
	v_cmp_gt_u32_e64 s[4:5], s33, v2
	v_or_b32_e32 v2, s2, v1
	s_bfe_u32 s90, s9, 0x20006
	v_writelane_b32 v254, s4, 1
	s_or_b32 s91, s90, 16
	v_and_b32_e32 v3, 48, v0
	v_writelane_b32 v254, s5, 2
	v_writelane_b32 v254, s2, 3
	s_movk_i32 s2, 0x110
	v_mul_lo_u32 v6, v2, s2
	v_lshlrev_b32_e32 v2, 2, v2
	s_add_i32 s4, 0, 0x11400
	v_add_u32_e32 v156, s3, v2
	v_add_u32_e32 v157, s4, v2
	v_or_b32_e32 v2, 64, v2
	v_add_u32_e32 v158, s3, v2
	v_add_u32_e32 v159, s4, v2
	s_lshr_b32 s5, s9, 8
	v_lshlrev_b32_e32 v2, 2, v1
	s_lshl_b32 s6, s5, 5
	v_lshl_or_b32 v2, s5, 7, v2
	v_writelane_b32 v254, s6, 4
	s_lshl_b32 s6, s90, 13
	v_or_b32_e32 v2, s90, v2
	s_add_u32 s6, s12, s6
	v_mul_lo_u32 v7, v2, s2
	v_lshlrev_b32_e32 v2, 2, v2
	s_addc_u32 s7, s13, 0
	v_add_u32_e32 v160, s3, v2
	v_add_u32_e32 v161, s4, v2
	v_or_b32_e32 v2, 0x100, v2
	s_add_u32 s86, s6, 0x10500000
	v_add_u32_e32 v162, s3, v2
	v_add_u32_e32 v163, s4, v2
	v_sub_u32_e32 v2, v1, v164
	s_addc_u32 s87, s7, 0
	v_cmp_gt_u32_e64 s[6:7], s33, v2
	v_sub_u32_e32 v2, v1, v165
	s_movk_i32 s5, 0x7f
	v_writelane_b32 v254, s6, 15
	v_or_b32_e32 v144, v115, v121
	v_add_u32_e32 v3, 0, v3
	v_writelane_b32 v254, s7, 16
	v_cmp_gt_u32_e64 s[6:7], s33, v2
	v_sub_u32_e32 v2, v1, v167
	v_lshlrev_b32_e32 v208, 3, v166
	v_writelane_b32 v254, s6, 46
	v_lshl_add_u32 v214, v0, 3, 0
	s_mov_b32 s77, 0
	v_writelane_b32 v254, s7, 47
	v_cmp_gt_u32_e64 s[6:7], s33, v2
	v_sub_u32_e32 v2, v1, v169
	v_or_b32_e32 v145, 0xffffff80, v114
	v_writelane_b32 v254, s6, 25
	v_or_b32_e32 v146, 0xffffffa0, v114
	v_or_b32_e32 v148, 32, v144
	v_writelane_b32 v254, s7, 26
	v_cmp_gt_u32_e64 s[6:7], s33, v2
	v_sub_u32_e32 v2, v1, v170
	v_or_b32_e32 v149, 64, v144
	v_writelane_b32 v254, s6, 21
	v_sub_u32_e32 v174, 0x6e, v114
	v_sub_u32_e32 v175, 0x6d, v114
	v_writelane_b32 v254, s7, 22
	v_cmp_gt_u32_e64 s[6:7], s33, v2
	v_sub_u32_e32 v2, v1, v171
	v_sub_u32_e32 v176, 0x6c, v114
	v_writelane_b32 v253, s6, 55
	v_sub_u32_e32 v177, 0x6b, v114
	v_sub_u32_e32 v178, 0x6a, v114
	v_writelane_b32 v253, s7, 56
	v_cmp_gt_u32_e64 s[6:7], s33, v2
	v_sub_u32_e32 v2, v1, v172
	v_sub_u32_e32 v179, 0x69, v114
	v_writelane_b32 v254, s6, 9
	v_sub_u32_e32 v180, 0x68, v114
	v_sub_u32_e32 v181, 0x4f, v114
	v_writelane_b32 v254, s7, 10
	v_cmp_gt_u32_e64 s[6:7], s33, v2
	v_sub_u32_e32 v2, v1, v173
	v_sub_u32_e32 v182, 0x4e, v114
	v_writelane_b32 v254, s6, 23
	v_sub_u32_e32 v183, 0x4d, v114
	v_sub_u32_e32 v184, 0x4c, v114
	v_writelane_b32 v254, s7, 24
	v_cmp_gt_u32_e64 s[6:7], s33, v2
	v_sub_u32_e32 v2, v1, v197
	v_sub_u32_e32 v185, 0x4b, v114
	v_writelane_b32 v254, s6, 33
	v_sub_u32_e32 v186, 0x4a, v114
	v_sub_u32_e32 v187, 0x49, v114
	v_writelane_b32 v254, s7, 34
	v_cmp_gt_u32_e64 s[6:7], s33, v2
	v_sub_u32_e32 v2, v1, v198
	v_sub_u32_e32 v188, 0x48, v114
	v_writelane_b32 v253, s6, 50
	v_sub_u32_e32 v189, 47, v114
	v_sub_u32_e32 v190, 46, v114
	v_writelane_b32 v253, s7, 51
	v_cmp_gt_u32_e64 s[6:7], s33, v2
	v_sub_u32_e32 v2, v1, v199
	v_readlane_b32 s16, v253, 33
	v_writelane_b32 v254, s6, 62
	v_readlane_b32 s17, v253, 34
	v_readlane_b32 s18, v253, 35
	v_writelane_b32 v254, s7, 63
	v_cmp_gt_u32_e64 s[6:7], s33, v2
	v_sub_u32_e32 v2, v1, v200
	v_readlane_b32 s19, v253, 36
	v_writelane_b32 v255, s6, 0
	v_readlane_b32 s20, v253, 37
	v_readlane_b32 s21, v253, 38
	v_writelane_b32 v255, s7, 1
	v_cmp_gt_u32_e64 s[6:7], s33, v2
	v_sub_u32_e32 v2, v1, v201
	v_readlane_b32 s22, v253, 39
	v_writelane_b32 v255, s6, 2
	v_readlane_b32 s23, v253, 40
	v_readlane_b32 s24, v253, 41
	v_writelane_b32 v255, s7, 3
	v_cmp_gt_u32_e64 s[6:7], s33, v2
	v_sub_u32_e32 v2, v1, v202
	v_readlane_b32 s25, v253, 42
	v_writelane_b32 v255, s6, 4
	v_readlane_b32 s26, v253, 43
	v_readlane_b32 s27, v253, 44
	v_writelane_b32 v255, s7, 5
	v_cmp_gt_u32_e64 s[6:7], s33, v2
	v_sub_u32_e32 v2, v1, v203
	v_readlane_b32 s28, v253, 45
	v_writelane_b32 v255, s6, 6
	v_readlane_b32 s29, v253, 46
	v_readlane_b32 s30, v253, 47
	v_writelane_b32 v255, s7, 7
	v_cmp_gt_u32_e64 s[6:7], s33, v2
	v_sub_u32_e32 v2, v1, v204
	v_readlane_b32 s31, v253, 48
	v_writelane_b32 v255, s6, 8
	s_mov_b64 s[16:17], s[24:25]
	s_mov_b64 s[22:23], s[30:31]
	v_writelane_b32 v255, s7, 9
	v_cmp_gt_u32_e64 s[6:7], s33, v2
	v_readlane_b32 s84, v253, 5
	v_lshlrev_b32_e32 v2, 5, v5
	v_writelane_b32 v255, s6, 10
	v_readlane_b32 s85, v253, 6
	v_lshlrev_b32_e32 v128, 1, v2
	v_writelane_b32 v255, s7, 11
	v_cmp_eq_u32_e64 s[6:7], 0, v5
	v_add_u32_e32 v5, s8, v4
	v_mul_lo_u32 v9, v5, s2
	v_writelane_b32 v255, s6, 12
	v_lshlrev_b32_e32 v5, 2, v5
	v_add_u32_e32 v216, s3, v5
	v_writelane_b32 v255, s7, 13
	s_add_u32 s6, s12, 0x23700000
	s_addc_u32 s7, s13, 0
	v_writelane_b32 v255, s6, 14
	v_add_u32_e32 v217, s4, v5
; #define LAS __attribute__((address_space(3)))
; __device__ __forceinline__ void phase4(const Args& a, LAS unsigned char* lds, int tid, int wave, int lane, int vcu, int G) {
;     ...
;     LAS float* O = (LAS float*)lds; LAS float* Mx = O + 256 * 68; LAS float* Ls = Mx + 256;
;     for (int u = vcu; u < 256 + 512; u += G) {
;         if (u < 256) {
;             LAS float* DEC = (LAS float*)lds; LAS float* SCL = DEC + 128;
;             const float* CH = (const float*)(ws + WS_CH); float* MPREV = (float*)(ws + WS_CH) + 2048;
;             const int hd = u >> 6;
;             __syncthreads();
;             if (wave == 0) {
;                 const int c0 = 2 * lane; const float b0 = CH[c0 * 4 + hd], a0 = b0 + CH[1024 + c0 * 4 + hd], b1 = CH[(c0 + 1) * 4 + hd], a1 = b1 + CH[1024 + (c0 + 1) * 4 + hd];
;                 float pa = fmaxf(a1, b1 + a0), pb = b0 + b1;
; #pragma unroll
;                 for (int o = 1; o < 64; o <<= 1) { const float qa = __shfl_up(pa, o), qb = __shfl_up(pb, o); if (lane >= o) { pa = fmaxf(pa, pb + qa); pb = pb + qb; } }
;                 const float mend = fmaxf(pa, pb);
;                 float mprev0 = __shfl_up(mend, 1); if (lane == 0) mprev0 = 0.f;
;                 const float mmid = fmaxf(a0, b0 + mprev0);
;                 DEC[c0] = __expf(b0 + mprev0 - mmid); SCL[c0] = __expf(a0 - mmid); DEC[c0 + 1] = __expf(b1 + mmid - mend); SCL[c0 + 1] = __expf(a1 - mend);
;                 if ((u & 63) == 0) { MPREV[c0 * 4 + hd] = mprev0; MPREV[(c0 + 1) * 4 + hd] = mmid; if (lane == 63) a.out[O_MP + hd] = mend; }
;             }
	v_mbcnt_lo_u32_b32 v2, -1, 0
	v_writelane_b32 v255, s7, 15
	s_add_u32 s6, s12, 0xb02000
	s_addc_u32 s7, s13, 0
	v_writelane_b32 v255, s6, 16
	s_cmp_lt_u32 s9, 64
	v_sub_u32_e32 v191, 45, v114
	v_writelane_b32 v255, s7, 17
	s_cselect_b64 s[6:7], -1, 0
	v_writelane_b32 v255, s6, 18
	v_sub_u32_e32 v192, 44, v114
	v_sub_u32_e32 v193, 43, v114
	v_writelane_b32 v255, s7, 19
	s_add_u32 s6, s12, 0xb00000
	s_addc_u32 s7, s13, 0
	v_writelane_b32 v255, s6, 20
	v_sub_u32_e32 v194, 42, v114
	v_sub_u32_e32 v195, 41, v114
	v_writelane_b32 v255, s7, 21
	v_cmp_eq_u32_e64 s[6:7], 0, v166
	v_sub_u32_e32 v196, 40, v114
	v_lshl_add_u32 v206, v205, 2, s4
	v_writelane_b32 v255, s6, 22
	v_add_u32_e32 v212, 0, v208
	v_lshlrev_b32_e32 v120, 1, v8
	v_writelane_b32 v255, s7, 23
	v_cmp_eq_u32_e64 s[6:7], 63, v166
	v_lshlrev_b32_e32 v215, 5, v213
	v_add_u32_e32 v221, 0x2000, v214
	v_writelane_b32 v255, s6, 24
	s_movk_i32 s89, 0x1400
	s_mov_b32 s81, 0x88000
	v_writelane_b32 v255, s7, 25
	s_add_u32 s6, s12, 0x1e200000
	s_addc_u32 s7, s13, 0
	v_writelane_b32 v255, s6, 26
	s_mov_b32 s88, 0x110000
	s_mov_b32 s64, 0x198000
	v_writelane_b32 v255, s7, 27
	s_movk_i32 s6, 0x80
	v_cmp_gt_u32_e64 s[6:7], s6, v0
	s_mov_b32 s65, 0xf149f2ca
	s_mov_b32 s78, 0xefa18f08
	v_writelane_b32 v255, s6, 28
	s_movk_i32 s79, 0x7fff
	s_mov_b32 s80, 0xffff0000
	v_writelane_b32 v255, s7, 29
	v_cmp_lt_u32_e64 s[6:7], s5, v0
	s_lshl_b32 s5, s8, 11
	v_lshlrev_b32_e32 v130, 2, v0
	v_writelane_b32 v255, s6, 30
	v_mbcnt_hi_u32_b32 v225, -1, v2
	v_mov_b32_e32 v226, 0xf149f2ca
	v_writelane_b32 v255, s7, 31
	v_cmp_eq_u32_e64 s[6:7], 3, v213
	v_add_u32_e32 v227, v3, v6
	v_add_u32_e32 v228, v3, v7
	v_writelane_b32 v255, s6, 32
	v_mov_b32_e32 v229, 0x200
	v_mov_b32_e32 v230, 0x240
	v_writelane_b32 v255, s7, 33
	s_add_u32 s6, s0, s5
	s_addc_u32 s7, s1, 0
	v_writelane_b32 v255, s6, 34
	v_mov_b32_e32 v231, 0x400
	v_mov_b32_e32 v232, 0x440
	v_writelane_b32 v255, s7, 35
	s_add_i32 s6, s8, 8
	s_lshl_b32 s5, s6, 11
	s_add_u32 s0, s0, s5
	s_addc_u32 s1, s1, 0
	v_writelane_b32 v255, s0, 36
	v_add_u32_e32 v4, s6, v4
	v_mul_lo_u32 v10, v4, s2
	v_writelane_b32 v255, s1, 37
	v_writelane_b32 v255, s6, 38
	v_cmp_gt_u32_e64 s[0:1], 2, v166
	v_lshlrev_b32_e32 v4, 2, v4
	v_add_u32_e32 v218, s3, v4
	v_writelane_b32 v255, s0, 39
	v_add_u32_e32 v219, s4, v4
	v_mad_u32_u24 v4, v8, 12, 0
	v_writelane_b32 v255, s1, 40
	v_cmp_gt_u32_e64 s[0:1], 4, v166
	v_add_u32_e32 v220, 0x400, v4
	v_add_u32_e32 v223, v3, v10
	v_writelane_b32 v255, s0, 41
	v_mov_b32_e32 v233, 0x600
	v_mov_b32_e32 v234, 0x640
	v_writelane_b32 v255, s1, 42
	v_cmp_gt_u32_e64 s[0:1], 8, v166
	v_mov_b32_e32 v235, 0x800
	v_mov_b32_e32 v236, 0x840
	v_writelane_b32 v255, s0, 43
	s_mov_b64 s[18:19], s[26:27]
	s_mov_b64 s[20:21], s[28:29]
	v_writelane_b32 v255, s1, 44
	v_cmp_gt_u32_e64 s[0:1], 32, v166
	s_nop 1
	v_writelane_b32 v255, s0, 45
	s_nop 1
	v_writelane_b32 v255, s1, 46
	s_add_u32 s0, s22, 0x5000000
	s_addc_u32 s1, s23, 0
	v_writelane_b32 v255, s0, 47
	s_ashr_i32 s85, s84, 31
	s_ashr_i32 s11, s10, 31
	v_writelane_b32 v255, s1, 48
	s_lshl_b64 s[0:1], s[84:85], 9
	v_lshl_add_u64 v[4:5], v[116:117], 0, s[0:1]
	s_mov_b32 s0, s10
	v_writelane_b32 v253, s0, 2
	v_lshl_or_b32 v4, v8, 2, v4
	v_lshl_add_u64 v[124:125], s[12:13], 0, v[4:5]
	v_writelane_b32 v253, s1, 3
	s_lshl_b64 s[0:1], s[10:11], 9
	v_writelane_b32 v254, s0, 11
	v_and_b32_e32 v4, 0x180, v0
	v_add_u32_e32 v222, 0, v4
	v_writelane_b32 v254, s1, 12
	v_lshl_add_u64 v[4:5], s[12:13], 0, v[122:123]
	s_mov_b64 s[0:1], 0x21307800
	v_writelane_b32 v254, s34, 37
	v_lshl_add_u64 v[126:127], v[4:5], 0, s[0:1]
	s_mov_b32 s0, s84
	v_writelane_b32 v254, s35, 38
	v_writelane_b32 v253, s0, 5
	v_writelane_b32 v254, s94, 39
	v_add_u32_e32 v123, v3, v9
	v_writelane_b32 v253, s1, 6
	v_writelane_b32 v254, s95, 40
	s_branch .LBB0_969

; #define LAS __attribute__((address_space(3)))
; __device__ __forceinline__ void phase5(const Args& a, LAS unsigned char* lds, int tid, int wave, int lane, int vcu, int G, int pmode) {
;     unsigned char* ws = a.ws;
;     const bf16* P1 = (const bf16*)(ws + WS_P1); const bf16* PT = (const bf16*)(ws + WS_PT); const bf16* CPREV = (const bf16*)(ws + WS_CPREV);
;     const float* NPREV = (const float*)(ws + WS_NPREV); const float* MPREV = (const float*)(ws + WS_CH) + 2048;
;     const float* BS = (const float*)(ws + WS_BS); const float* CMB = (const float*)(ws + WS_CMB); const float* IG = (const float*)(ws + WS_IG);
;     bf16* HM = pmode ? (bf16*)(ws + WS_QP) : (bf16*)(ws + WS_HM); float* SSM = pmode ? (float*)(ws + WS_QP + 32 * MiB) : (float*)(ws + WS_SSM);
;     const int i16 = lane & 15, g = lane >> 4;
;     LAS unsigned char* LK = lds; LAS unsigned char* LV = lds + 34816; LAS unsigned char* LC = lds + 69632;
;     LAS float* LB = (LAS float*)(lds + 104448);
;     for (int u = vcu; u < 512; u += G) {
;         const int c = u >> 2, hd = u & 3, tg = wave, tl = 16 * tg + i16; const size_t t = (size_t)128 * c + tl;
;     ...
;         nq += __shfl_xor(nq, 16); nq += __shfl_xor(nq, 32);
;         dsum += __shfl_xor(dsum, 16); dsum += __shfl_xor(dsum, 32);
;         const float den = dsum + aint * nq, inv = 1.f / fmaxf(fabsf(den), __expf(-m_t));
;         float ssq = 0.f;
;         LAS unsigned char* LO = lds + 104960 + wave * (16 * 264);
.LBB0_1059:
	s_or_b64 exec, exec, s[2:3]
	s_waitcnt lgkmcnt(0)
	s_barrier
	s_branch .Lpin_4
	.p2align 8
	s_nop 0
	s_nop 0
	s_nop 0
.Lpin_4:
.LBB0_1060:
	s_cmp_lt_i32 s86, 6
	s_cselect_b64 s[18:19], -1, 0
	s_and_b64 s[0:1], s[18:19], s[0:1]
	s_andn2_b64 vcc, exec, s[0:1]
	s_cbranch_vccnz .LBB0_1083
	v_readlane_b32 s0, v253, 5
	s_cmpk_gt_i32 s0, 0x1ff
	v_readlane_b32 s1, v253, 6
	s_cbranch_scc1 .LBB0_1082
	s_add_u32 s20, s84, 0x7d00000
	s_addc_u32 s21, s85, 0
	s_add_u32 s33, s84, 0xb02000
	s_addc_u32 s44, s85, 0
	s_add_u32 s22, s84, 0x900000
	s_addc_u32 s23, s85, 0
	s_add_u32 s24, s84, 0xa00000
	s_addc_u32 s25, s85, 0
	s_add_u32 s26, s84, 0x700000
	s_addc_u32 s27, s85, 0
	s_add_u32 s28, s84, 0x23800000
	v_readlane_b32 s0, v253, 27
	s_addc_u32 s29, s85, 0
	s_mov_b32 s4, s0
	s_add_i32 s2, 0, 0x19800
	v_lshl_add_u32 v131, v0, 2, s2
	s_mul_i32 s2, s4, 0x1080
	s_add_i32 s2, s2, 0
	s_waitcnt vmcnt(0)
	v_and_b32_e32 v3, 15, v0
	v_mov_b32_e32 v135, 0
	s_add_i32 s2, s2, 0x19a00
	s_movk_i32 s3, 0x108
	v_mov_b32_e32 v1, s2
	v_lshlrev_b32_e32 v138, 4, v3
	v_mov_b32_e32 v139, v135
	v_mad_u32_u24 v7, v3, s3, v1
	v_lshl_add_u64 v[4:5], s[84:85], 0, v[138:139]
	s_mov_b64 s[4:5], 0x20300000
	v_mbcnt_lo_u32_b32 v1, -1, 0
	v_add_u32_e32 v8, s2, v138
	s_mov_b64 s[2:3], 0x22600000
	v_lshl_add_u64 v[142:143], v[4:5], 0, s[4:5]
	s_mov_b64 s[4:5], 0xd200000
	v_mbcnt_hi_u32_b32 v1, -1, v1
	v_lshl_add_u64 v[140:141], v[4:5], 0, s[2:3]
	v_lshl_add_u64 v[144:145], v[4:5], 0, s[4:5]
	v_and_b32_e32 v5, 64, v1
	v_xor_b32_e32 v4, 16, v1
	v_add_u32_e32 v5, 64, v5
	v_cmp_lt_i32_e32 vcc, v4, v5
	v_lshrrev_b32_e32 v149, 4, v0
	s_mov_b64 s[4:5], 0x7d01000
	v_cndmask_b32_e32 v4, v1, v4, vcc
	v_lshlrev_b32_e32 v139, 2, v4
	v_xor_b32_e32 v4, 32, v1
	v_cmp_lt_i32_e32 vcc, v4, v5
	v_mul_hi_u32_u24_e32 v5, 0x1400, v149
	s_lshl_b32 s45, s0, 4
	v_cndmask_b32_e32 v1, v1, v4, vcc
	v_mul_u32_u24_e32 v4, 0x1400, v149
	v_or_b32_e32 v4, v4, v138
	v_lshl_add_u64 v[4:5], s[84:85], 0, v[4:5]
	v_lshl_add_u64 v[154:155], v[4:5], 0, s[4:5]
	v_readlane_b32 s4, v253, 5
	v_readlane_b32 s5, v253, 6
	s_mov_b32 s40, s4
	s_ashr_i32 s41, s4, 31
	s_lshr_b32 s47, s93, 7
	s_movk_i32 s6, 0x110
	s_lshl_b64 s[4:5], s[40:41], 9
	v_or_b32_e32 v132, s45, v3
	v_mul_u32_u24_e32 v9, 0x110, v3
	v_mad_u32_u24 v167, v3, s6, 0
	v_lshlrev_b32_e32 v3, 1, v0
	s_add_u32 s4, s84, s4
	v_and_b32_e32 v134, 0x60, v3
	s_addc_u32 s5, s85, s5
	v_lshl_add_u64 v[4:5], s[4:5], 0, v[134:135]
	s_mov_b64 s[4:5], 0x21300080
	v_lshl_add_u64 v[156:157], v[4:5], 0, s[4:5]
	v_readlane_b32 s4, v253, 2
	v_or_b32_e32 v10, 48, v166
	v_or_b32_e32 v12, 0x70, v166
	v_readlane_b32 s5, v253, 3
	v_readlane_b32 s1, v253, 28
	v_mad_u32_u24 v151, v12, s6, 0
	v_mad_u32_u24 v153, v10, s6, 0
	s_mov_b32 s6, s4
	s_ashr_i32 s7, s4, 31
	v_writelane_b32 v253, s4, 2
	v_lshrrev_b32_e32 v130, 4, v166
	v_and_b32_e32 v6, 3, v0
	v_writelane_b32 v253, s5, 3
	v_bfe_u32 v3, v0, 2, 2
	s_mov_b32 s4, s40
	s_movk_i32 s0, 0x7f
	v_lshlrev_b32_e32 v136, 3, v130
	v_lshlrev_b32_e32 v2, 2, v130
	v_and_b32_e32 v137, 48, v0
	v_mul_u32_u24_e32 v11, 0x110, v10
	v_mul_u32_u24_e32 v13, 0x110, v12
	v_mul_u32_u24_e32 v14, 0x108, v130
	v_readlane_b32 s93, v253, 49
	s_mov_b32 s48, 0x8800
	v_mul_u32_u24_e32 v3, 0x880, v3
	v_mul_u32_u24_e32 v4, 0x110, v6
	v_writelane_b32 v253, s4, 5
	s_mov_b32 s31, 0
	v_mov_b32_e32 v133, v135
	v_cmp_lt_u32_e64 s[0:1], s0, v0
	v_cmp_gt_u32_e64 s[2:3], 16, v166
	v_or_b32_e32 v146, 4, v130
	v_or_b32_e32 v148, 8, v130
	v_or_b32_e32 v150, 12, v130
	v_lshlrev_b32_e32 v147, 2, v1
	v_mov_b32_e32 v152, v132
	v_mov_b32_e32 v1, v132
	s_movk_i32 s46, 0x1400
	s_lshl_b64 s[34:35], s[6:7], 9
	s_add_i32 s47, s47, 1
	v_add3_u32 v169, v13, v137, s48
	v_add3_u32 v188, v11, v137, s48
	v_add3_u32 v189, v9, v137, s48
	v_add3_u32 v190, v3, v4, v137
	v_lshlrev_b32_e32 v191, 5, v130
	s_movk_i32 s49, 0x7ff
	s_mov_b64 s[36:37], 0x28000
	s_movk_i32 s50, 0x15ff
	v_lshlrev_b32_e32 v158, 1, v136
	v_lshlrev_b32_e32 v160, 1, v2
	s_mov_b32 s51, 0x5040100
	s_mov_b32 s52, 0xffff0000
	s_mov_b64 s[38:39], 0x100
	s_movk_i32 s53, 0x7fff
	v_add_u32_e32 v192, v7, v136
	v_add_u32_e32 v193, v8, v14
	v_mov_b32_e32 v194, 1
	s_mov_b32 s54, s40
	v_writelane_b32 v253, s5, 6
	s_branch .LBB0_1064

; #define LAS __attribute__((address_space(3)))
; __device__ __forceinline__ f32x4 mfma16(bf16x8 a, bf16x8 b, f32x4 c) { return __builtin_amdgcn_mfma_f32_16x16x32_bf16(a, b, c, 0, 0, 0); }
; __device__ __forceinline__ void phase5(const Args& a, LAS unsigned char* lds, int tid, int wave, int lane, int vcu, int G, int pmode) {
;     ...
;         if (!(pmode & 2)) for (int x = tid; x < 3 * 128 * 16; x += NTHREADS) {
;             const int mat = x >> 11, row = (x >> 4) & 127, ch = x & 15;
;             const bf16* src = mat == 0 ? P1 + ((size_t)128 * c + row) * P1W + C_MK + hd * 128 + 8 * ch
;                             : mat == 1 ? PT + (size_t)(R_MVT + hd * 128 + row) * MT + 128 * c + 8 * ch
;                                        : CPREV + ((size_t)(c * 4 + hd) * 128 + row) * 128 + 8 * ch;
;             *(LAS u32x4*)(lds + mat * 34816 + row * 272 + 16 * ch) = *(const u32x4*)src;
;         }
;         if (tid < 128) LB[tid] = BS[((size_t)128 * c + tid) * 4 + hd];
;         const float mprev = MPREV[c * 4 + hd], bmax = fmaxf(mprev, CMB[t * 4 + hd]), aint = __expf(mprev - bmax), m_t = (IG[t * 4 + hd] - BS[t * 4 + hd]) + bmax;
;         bf16x8 qf[4];
; #pragma unroll
;         for (int ks = 0; ks < 4; ++ks) qf[ks] = ldfrag(P1 + t * P1W + C_MQ + hd * 128 + 32 * ks + 8 * g);
;         u32x2 mo[8];
; #pragma unroll
;         for (int d = 0; d < 8; ++d) mo[d] = *(const u32x2*)(P1 + t * P1W + C_MO + hd * 128 + 16 * d + 4 * g);
;         __syncthreads();
;         f32x4 an[8], ac[8];
; #pragma unroll
;         for (int d = 0; d < 8; ++d) { an[d] = (f32x4){0.f, 0.f, 0.f, 0.f}; ac[d] = an[d]; }
;         float nq = 0.f;
; #pragma unroll 2
;         for (int ks = 0; ks < ((pmode & 4) ? 0 : 4); ++ks) {
; #pragma unroll
;             for (int d = 0; d < 8; ++d) ac[d] = mfma16(*(const LAS bf16x8*)(LC + (16 * d + i16) * 272 + 64 * ks + 16 * g), qf[ks], ac[d]);
.LBB0_1076:
	s_or_b64 exec, exec, s[6:7]
	s_waitcnt vmcnt(0)
	ds_write_b128 v48, v[8:11]
	ds_write_b128 v48, v[12:15] offset:8704
	ds_write_b128 v48, v[16:19] offset:17408
	ds_write_b128 v48, v[20:23] offset:26112
	ds_write_b128 v48, v[24:27] offset:34816
	ds_write_b128 v48, v[28:31] offset:43520
	ds_write_b128 v48, v[32:35] offset:52224
	ds_write_b128 v48, v[36:39] offset:60928
	ds_write_b128 v49, v[40:43] offset:34816
	ds_write_b128 v49, v[44:47] offset:43520
	ds_write_b128 v49, v[172:175] offset:52224
	ds_write_b128 v49, v[176:179] offset:60928
	s_lshl_b64 s[4:5], s[40:41], 2
	s_add_u32 s4, s33, s4
	v_lshl_add_u64 v[4:5], s[42:43], 0, v[132:133]
	s_addc_u32 s5, s44, s5
	v_mov_b64_e32 v[10:11], s[20:21]
	global_load_dword v134, v135, s[4:5]
	v_lshlrev_b64 v[6:7], 2, v[4:5]
	v_mad_u64_u32 v[10:11], s[4:5], v4, s46, v[10:11]
	v_or_b32_e32 v163, v3, v7
	v_or_b32_e32 v162, v2, v6
	v_mad_i32_i24 v11, v5, s46, v11
	s_lshl_b32 s30, s12, 1
	v_lshlrev_b64 v[2:3], 2, v[162:163]
	v_lshl_add_u64 v[14:15], v[10:11], 0, s[30:31]
	v_mov_b32_e32 v159, v135
	v_lshl_add_u64 v[6:7], s[24:25], 0, v[2:3]
	v_lshl_add_u64 v[8:9], s[26:27], 0, v[2:3]
	v_lshl_add_u64 v[2:3], s[22:23], 0, v[2:3]
	v_lshl_add_u64 v[16:17], v[14:15], 0, v[158:159]
	v_mov_b32_e32 v161, v135
	global_load_dword v49, v[6:7], off
	global_load_dword v159, v[8:9], off
	global_load_dword v195, v[2:3], off
	s_nop 0
	global_load_dwordx4 v[2:5], v[16:17], off offset:2048
	global_load_dwordx4 v[6:9], v[16:17], off offset:2112
	global_load_dwordx4 v[10:13], v[16:17], off offset:2176
	v_lshl_add_u64 v[18:19], v[14:15], 0, v[160:161]
	global_load_dwordx4 v[14:17], v[16:17], off offset:2240
	s_nop 0
	global_load_dwordx2 v[182:183], v[18:19], off offset:3072
	global_load_dwordx2 v[180:181], v[18:19], off offset:3104
	global_load_dwordx2 v[178:179], v[18:19], off offset:3136
	global_load_dwordx2 v[176:177], v[18:19], off offset:3168
	global_load_dwordx2 v[174:175], v[18:19], off offset:3200
	global_load_dwordx2 v[172:173], v[18:19], off offset:3232
	global_load_dwordx2 v[170:171], v[18:19], off offset:3264
	global_load_dwordx2 v[164:165], v[18:19], off offset:3296
	v_mov_b32_e32 v184, 0
	s_mov_b64 s[4:5], 15
	v_mov_b64_e32 v[186:187], v[156:157]
	v_mov_b32_e32 v185, v167
	v_mov_b32_e32 v196, v153
	v_mov_b32_e32 v197, v151
	v_mov_b32_e32 v18, 0
	v_mov_b32_e32 v22, 0
	v_mov_b32_e32 v26, 0
	v_mov_b32_e32 v30, 0
	v_mov_b32_e32 v34, 0
	v_mov_b32_e32 v38, 0
	v_mov_b32_e32 v42, 0
	v_mov_b32_e32 v46, 0
	v_mov_b32_e32 v19, v184
	v_mov_b32_e32 v20, v184
	v_mov_b32_e32 v21, v184
	v_mov_b32_e32 v23, v184
	v_mov_b32_e32 v24, v184
	v_mov_b32_e32 v25, v184
	v_mov_b32_e32 v27, v184
	v_mov_b32_e32 v28, v184
	v_mov_b32_e32 v29, v184
	v_mov_b32_e32 v31, v184
	v_mov_b32_e32 v32, v184
	v_mov_b32_e32 v33, v184
	v_mov_b32_e32 v35, v184
	v_mov_b32_e32 v36, v184
	v_mov_b32_e32 v37, v184
	v_mov_b32_e32 v39, v184
	v_mov_b32_e32 v40, v184
	v_mov_b32_e32 v41, v184
	v_mov_b32_e32 v43, v184
	v_mov_b32_e32 v44, v184
	v_mov_b32_e32 v45, v184
	v_mov_b32_e32 v47, v184
	v_mov_b32_e32 v48, v184
	s_waitcnt lgkmcnt(0)
	s_barrier
	s_waitcnt vmcnt(15)
	v_max_f32_e32 v50, v134, v134
	s_waitcnt vmcnt(14)
	v_max_f32_e32 v49, v49, v49
	v_max_f32_e32 v161, v50, v49
	v_mov_b32_e32 v49, v184
	v_add_u32_e32 v114, v185, v137
	v_add_u32_e32 v114, 0x11000, v114
	global_load_dwordx4 v[50:53], v[186:187], off offset:-128
	global_load_dwordx4 v[54:57], v[186:187], off offset:-112
	global_load_dwordx4 v[58:61], v[186:187], off
	global_load_dwordx4 v[62:65], v[186:187], off offset:16
	global_load_dwordx4 v[66:69], v[186:187], off offset:128
	global_load_dwordx4 v[70:73], v[186:187], off offset:144
	global_load_dwordx4 v[74:77], v[186:187], off offset:256
	global_load_dwordx4 v[78:81], v[186:187], off offset:272
	ds_read_b128 v[82:85], v114
	ds_read_b128 v[86:89], v114 offset:4352
	ds_read_b128 v[90:93], v114 offset:8704
	ds_read_b128 v[94:97], v114 offset:13056
	ds_read_b128 v[98:101], v114 offset:17408
	ds_read_b128 v[102:105], v114 offset:21760
	ds_read_b128 v[106:109], v114 offset:26112
	ds_read_b128 v[110:113], v114 offset:30464
	ds_read_b128 v[198:201], v114 offset:64
	ds_read_b128 v[202:205], v114 offset:4416
	ds_read_b128 v[206:209], v114 offset:8768
	ds_read_b128 v[210:213], v114 offset:13120
	ds_read_b128 v[214:217], v114 offset:17472
	ds_read_b128 v[218:221], v114 offset:21824
	ds_read_b128 v[222:225], v114 offset:26176
	ds_read_b128 v[226:229], v114 offset:30528
	s_waitcnt vmcnt(16)
	s_waitcnt lgkmcnt(8)
	v_mfma_f32_16x16x32_bf16 v[46:49], v[82:85], v[2:5], v[46:49]
	v_mfma_f32_16x16x32_bf16 v[42:45], v[86:89], v[2:5], v[42:45]
	v_mfma_f32_16x16x32_bf16 v[38:41], v[90:93], v[2:5], v[38:41]
	v_mfma_f32_16x16x32_bf16 v[34:37], v[94:97], v[2:5], v[34:37]
	v_mfma_f32_16x16x32_bf16 v[30:33], v[98:101], v[2:5], v[30:33]
	v_mfma_f32_16x16x32_bf16 v[26:29], v[102:105], v[2:5], v[26:29]
	v_mfma_f32_16x16x32_bf16 v[22:25], v[106:109], v[2:5], v[22:25]
	v_mfma_f32_16x16x32_bf16 v[18:21], v[110:113], v[2:5], v[18:21]
	ds_read_b128 v[82:85], v114 offset:128
	ds_read_b128 v[86:89], v114 offset:4480
	ds_read_b128 v[90:93], v114 offset:8832
	ds_read_b128 v[94:97], v114 offset:13184
	ds_read_b128 v[98:101], v114 offset:17536
	ds_read_b128 v[102:105], v114 offset:21888
	ds_read_b128 v[106:109], v114 offset:26240
	ds_read_b128 v[110:113], v114 offset:30592
	s_waitcnt lgkmcnt(8)
; #define LAS __attribute__((address_space(3)))
; __device__ __forceinline__ float bf_lo(unsigned w) { return __uint_as_float(w << 16); }
; __device__ __forceinline__ float bf_hi(unsigned w) { return __uint_as_float(w & 0xffff0000u); }
; __device__ __forceinline__ f32x4 mfma16(bf16x8 a, bf16x8 b, f32x4 c) { return __builtin_amdgcn_mfma_f32_16x16x32_bf16(a, b, c, 0, 0, 0); }
; __device__ __forceinline__ void phase5(const Args& a, LAS unsigned char* lds, int tid, int wave, int lane, int vcu, int G, int pmode) {
;     ...
;         for (int ks = 0; ks < ((pmode & 4) ? 0 : 4); ++ks) {
; #pragma unroll
;             for (int d = 0; d < 8; ++d) ac[d] = mfma16(*(const LAS bf16x8*)(LC + (16 * d + i16) * 272 + 64 * ks + 16 * g), qf[ks], ac[d]);
;             const u32x4 qw = __builtin_bit_cast(u32x4, qf[ks]); const float* np = NPREV + (size_t)(c * 4 + hd) * 128 + 32 * ks + 8 * g;
;             const f32x4 n0 = *(const f32x4*)np, n1 = *(const f32x4*)(np + 4);
;             nq += (bf_lo(qw.x) * n0[0] + bf_hi(qw.x) * n0[1]) + (bf_lo(qw.y) * n0[2] + bf_hi(qw.y) * n0[3]) + (bf_lo(qw.z) * n1[0] + bf_hi(qw.z) * n1[1]) + (bf_lo(qw.w) * n1[2] + bf_hi(qw.w) * n1[3]);
;         }
;         float dsum = 0.f;
;         const int nkb = (pmode & 4) ? 0 : (tg >> 1) + 1;
;         for (int kb = 0; kb < nkb; ++kb) {
	v_mfma_f32_16x16x32_bf16 v[46:49], v[198:201], v[6:9], v[46:49]
	v_mfma_f32_16x16x32_bf16 v[42:45], v[202:205], v[6:9], v[42:45]
	v_mfma_f32_16x16x32_bf16 v[38:41], v[206:209], v[6:9], v[38:41]
	v_mfma_f32_16x16x32_bf16 v[34:37], v[210:213], v[6:9], v[34:37]
	v_mfma_f32_16x16x32_bf16 v[30:33], v[214:217], v[6:9], v[30:33]
	v_mfma_f32_16x16x32_bf16 v[26:29], v[218:221], v[6:9], v[26:29]
	v_mfma_f32_16x16x32_bf16 v[22:25], v[222:225], v[6:9], v[22:25]
	v_mfma_f32_16x16x32_bf16 v[18:21], v[226:229], v[6:9], v[18:21]
	ds_read_b128 v[198:201], v114 offset:192
	ds_read_b128 v[202:205], v114 offset:4544
	ds_read_b128 v[206:209], v114 offset:8896
	ds_read_b128 v[210:213], v114 offset:13248
	ds_read_b128 v[214:217], v114 offset:17600
	ds_read_b128 v[218:221], v114 offset:21952
	ds_read_b128 v[222:225], v114 offset:26304
	ds_read_b128 v[226:229], v114 offset:30656
	s_waitcnt lgkmcnt(8)
	v_mfma_f32_16x16x32_bf16 v[46:49], v[82:85], v[10:13], v[46:49]
	v_mfma_f32_16x16x32_bf16 v[42:45], v[86:89], v[10:13], v[42:45]
	v_mfma_f32_16x16x32_bf16 v[38:41], v[90:93], v[10:13], v[38:41]
	v_mfma_f32_16x16x32_bf16 v[34:37], v[94:97], v[10:13], v[34:37]
	v_mfma_f32_16x16x32_bf16 v[30:33], v[98:101], v[10:13], v[30:33]
	v_mfma_f32_16x16x32_bf16 v[26:29], v[102:105], v[10:13], v[26:29]
	v_mfma_f32_16x16x32_bf16 v[22:25], v[106:109], v[10:13], v[22:25]
	v_mfma_f32_16x16x32_bf16 v[18:21], v[110:113], v[10:13], v[18:21]
	s_waitcnt lgkmcnt(0)
	v_mfma_f32_16x16x32_bf16 v[46:49], v[198:201], v[14:17], v[46:49]
	v_mfma_f32_16x16x32_bf16 v[42:45], v[202:205], v[14:17], v[42:45]
	v_mfma_f32_16x16x32_bf16 v[38:41], v[206:209], v[14:17], v[38:41]
	v_mfma_f32_16x16x32_bf16 v[34:37], v[210:213], v[14:17], v[34:37]
	v_mfma_f32_16x16x32_bf16 v[30:33], v[214:217], v[14:17], v[30:33]
	v_mfma_f32_16x16x32_bf16 v[26:29], v[218:221], v[14:17], v[26:29]
	v_mfma_f32_16x16x32_bf16 v[22:25], v[222:225], v[14:17], v[22:25]
	v_mfma_f32_16x16x32_bf16 v[18:21], v[226:229], v[14:17], v[18:21]
	s_waitcnt vmcnt(0)
	v_lshlrev_b32_e32 v115, 16, v2
	v_and_b32_e32 v119, 0xffff0000, v2
	v_mul_f32_e32 v115, v115, v50
	v_fmac_f32_e32 v115, v119, v51
	v_lshlrev_b32_e32 v116, 16, v3
	v_and_b32_e32 v119, 0xffff0000, v3
	v_mul_f32_e32 v116, v116, v52
	v_fmac_f32_e32 v116, v119, v53
	v_lshlrev_b32_e32 v117, 16, v4
	v_and_b32_e32 v119, 0xffff0000, v4
	v_mul_f32_e32 v117, v117, v54
	v_fmac_f32_e32 v117, v119, v55
	v_lshlrev_b32_e32 v118, 16, v5
	v_and_b32_e32 v119, 0xffff0000, v5
	v_mul_f32_e32 v118, v118, v56
	v_fmac_f32_e32 v118, v119, v57
	v_add_f32_e32 v115, v115, v116
	v_add_f32_e32 v115, v115, v117
	v_add_f32_e32 v115, v115, v118
	v_add_f32_e32 v184, v184, v115
	v_lshlrev_b32_e32 v115, 16, v6
	v_and_b32_e32 v119, 0xffff0000, v6
	v_mul_f32_e32 v115, v115, v58
	v_fmac_f32_e32 v115, v119, v59
	v_lshlrev_b32_e32 v116, 16, v7
	v_and_b32_e32 v119, 0xffff0000, v7
	v_mul_f32_e32 v116, v116, v60
	v_fmac_f32_e32 v116, v119, v61
	v_lshlrev_b32_e32 v117, 16, v8
	v_and_b32_e32 v119, 0xffff0000, v8
	v_mul_f32_e32 v117, v117, v62
	v_fmac_f32_e32 v117, v119, v63
	v_lshlrev_b32_e32 v118, 16, v9
	v_and_b32_e32 v119, 0xffff0000, v9
	v_mul_f32_e32 v118, v118, v64
	v_fmac_f32_e32 v118, v119, v65
	v_add_f32_e32 v115, v115, v116
	v_add_f32_e32 v115, v115, v117
	v_add_f32_e32 v115, v115, v118
	v_add_f32_e32 v184, v184, v115
	v_lshlrev_b32_e32 v115, 16, v10
	v_and_b32_e32 v119, 0xffff0000, v10
	v_mul_f32_e32 v115, v115, v66
	v_fmac_f32_e32 v115, v119, v67
	v_lshlrev_b32_e32 v116, 16, v11
	v_and_b32_e32 v119, 0xffff0000, v11
	v_mul_f32_e32 v116, v116, v68
	v_fmac_f32_e32 v116, v119, v69
	v_lshlrev_b32_e32 v117, 16, v12
	v_and_b32_e32 v119, 0xffff0000, v12
	v_mul_f32_e32 v117, v117, v70
	v_fmac_f32_e32 v117, v119, v71
	v_lshlrev_b32_e32 v118, 16, v13
	v_and_b32_e32 v119, 0xffff0000, v13
	v_mul_f32_e32 v118, v118, v72
	v_fmac_f32_e32 v118, v119, v73
	v_add_f32_e32 v115, v115, v116
	v_add_f32_e32 v115, v115, v117
	v_add_f32_e32 v115, v115, v118
	v_add_f32_e32 v184, v184, v115
	v_lshlrev_b32_e32 v115, 16, v14
	v_and_b32_e32 v119, 0xffff0000, v14
	v_mul_f32_e32 v115, v115, v74
	v_fmac_f32_e32 v115, v119, v75
	v_lshlrev_b32_e32 v116, 16, v15
	v_and_b32_e32 v119, 0xffff0000, v15
	v_mul_f32_e32 v116, v116, v76
	v_fmac_f32_e32 v116, v119, v77
	v_lshlrev_b32_e32 v117, 16, v16
	v_and_b32_e32 v119, 0xffff0000, v16
	v_mul_f32_e32 v117, v117, v78
	v_fmac_f32_e32 v117, v119, v79
	v_lshlrev_b32_e32 v118, 16, v17
	v_and_b32_e32 v119, 0xffff0000, v17
	v_mul_f32_e32 v118, v118, v80
	v_fmac_f32_e32 v118, v119, v81
	v_add_f32_e32 v115, v115, v116
	v_add_f32_e32 v115, v115, v117
	v_add_f32_e32 v115, v115, v118
	v_add_f32_e32 v184, v184, v115
	v_mov_b32_e32 v185, 0
	v_mov_b32_e32 v82, v191
	v_mov_b32_e32 v83, v136
	v_mov_b32_e32 v84, v190
	v_mov_b32_e32 v85, v189
	v_mov_b32_e32 v86, v188
	v_mov_b32_e32 v87, v169
	s_mov_b32 s41, s47
	v_mov_b32_e32 v50, v185
	v_mov_b32_e32 v51, v185
	v_mov_b32_e32 v52, v185
	v_mov_b32_e32 v53, v185
	v_mov_b32_e32 v54, v185
	v_mov_b32_e32 v55, v185
	v_mov_b32_e32 v56, v185
	v_mov_b32_e32 v57, v185
	v_mov_b32_e32 v58, v185
	v_mov_b32_e32 v59, v185
	v_mov_b32_e32 v60, v185
	v_mov_b32_e32 v61, v185
	v_mov_b32_e32 v62, v185
	v_mov_b32_e32 v63, v185
	v_mov_b32_e32 v64, v185
	v_mov_b32_e32 v65, v185
	v_mov_b32_e32 v66, v185
	v_mov_b32_e32 v67, v185
	v_mov_b32_e32 v68, v185
	v_mov_b32_e32 v69, v185
	v_mov_b32_e32 v70, v185
	v_mov_b32_e32 v71, v185
	v_mov_b32_e32 v72, v185
	v_mov_b32_e32 v73, v185
	v_mov_b32_e32 v74, v185
	v_mov_b32_e32 v75, v185
	v_mov_b32_e32 v76, v185
	v_mov_b32_e32 v77, v185
	v_mov_b32_e32 v78, v185
	v_mov_b32_e32 v79, v185
	v_mov_b32_e32 v80, v185
	v_mov_b32_e32 v81, v185
	s_branch .Lpin_5
	.p2align 8
	s_nop 0
	s_nop 0
	s_nop 0
	s_nop 0
	s_nop 0
	s_nop 0
	s_nop 0
	s_nop 0
	s_nop 0
	s_nop 0
	s_nop 0
	s_nop 0
	s_nop 0
	s_nop 0
	s_nop 0
	s_nop 0
	s_nop 0
	s_nop 0
	s_nop 0
	s_nop 0
	s_nop 0
	s_nop 0
	s_nop 0
	s_nop 0
	s_nop 0
; #define LAS __attribute__((address_space(3)))
; __device__ __forceinline__ f32x4 mfma16(bf16x8 a, bf16x8 b, f32x4 c) { return __builtin_amdgcn_mfma_f32_16x16x32_bf16(a, b, c, 0, 0, 0); }
; __device__ __forceinline__ bf16x8 pack8(f32x4 a, f32x4 b) { u32x4 w; w.x = pk2(a[0], a[1]); w.y = pk2(a[2], a[3]); w.z = pk2(b[0], b[1]); w.w = pk2(b[2], b[3]); return __builtin_bit_cast(bf16x8, w); }
; __device__ __forceinline__ void phase5(const Args& a, LAS unsigned char* lds, int tid, int wave, int lane, int vcu, int G, int pmode) {
;     ...
;         for (int kb = 0; kb < nkb; ++kb) {
;             f32x4 p[2];
; #pragma unroll
;             for (int hf = 0; hf < 2; ++hf) {
;                 const int s = 32 * kb + 8 * (i16 >> 2) + (i16 & 3) + 4 * hf;
;                 f32x4 acc = {0.f, 0.f, 0.f, 0.f};
; #pragma unroll
;                 for (int ks = 0; ks < 4; ++ks) acc = mfma16(*(const LAS bf16x8*)(LK + s * 272 + 64 * ks + 16 * g), qf[ks], acc);
;                 const f32x4 b4 = *(const LAS f32x4*)(LB + 32 * kb + 8 * g + 4 * hf);
; #pragma unroll
;                 for (int e = 0; e < 4; ++e) { const int sl = 32 * kb + 8 * g + 4 * hf + e; const float w = sl <= tl ? __expf(b4[e] - bmax) : 0.f; const float pv = acc[e] * w; p[hf][e] = pv; dsum += pv; }
;             }
;             const bf16x8 pf = pack8(p[0], p[1]);
; #pragma unroll
;             for (int d = 0; d < 8; ++d) an[d] = mfma16(*(const LAS bf16x8*)(LV + (16 * d + i16) * 272 + 64 * kb + 16 * g), pf, an[d]);
;         }
.Lpin_5:
.LBB0_1079:
	v_add_u32_e32 v116, 0, v82
	v_add_u32_e32 v124, 0, v84
	v_add_u32_e32 v206, 0, v85
	v_add_u32_e32 v196, 0x19800, v116
	v_add_u32_e32 v200, 0x19810, v116
	ds_read_b128 v[88:91], v124 offset:64
	ds_read_b128 v[92:95], v124 offset:128
	ds_read_b128 v[96:99], v124 offset:192
	ds_read_b128 v[100:103], v124 offset:1088
	ds_read_b128 v[104:107], v124 offset:1152
	ds_read_b128 v[108:111], v124 offset:1216
	ds_read_b128 v[112:115], v124 offset:1280
	ds_read_b128 v[116:119], v206
	ds_read_b128 v[120:123], v206 offset:4352
	ds_read_b128 v[124:127], v124
	ds_read_b128 v[196:199], v196
	ds_read_b128 v[200:203], v200
	s_waitcnt lgkmcnt(2)
	v_mfma_f32_16x16x32_bf16 v[124:127], v[124:127], v[2:5], 0
	s_waitcnt lgkmcnt(1)
	v_sub_f32_e32 v196, v196, v161
	s_waitcnt lgkmcnt(0)
	v_sub_f32_e32 v201, v201, v161
	v_sub_f32_e32 v203, v203, v161
	v_mfma_f32_16x16x32_bf16 v[100:103], v[100:103], v[2:5], 0
	v_sub_f32_e32 v197, v197, v161
	v_sub_f32_e32 v198, v198, v161
	v_sub_f32_e32 v199, v199, v161
	v_mfma_f32_16x16x32_bf16 v[88:91], v[88:91], v[6:9], v[124:127]
	v_sub_f32_e32 v200, v200, v161
	v_mul_f32_e32 v201, 0x3fb8aa3b, v201
	v_mul_f32_e32 v203, 0x3fb8aa3b, v203
	v_mfma_f32_16x16x32_bf16 v[100:103], v[104:107], v[6:9], v[100:103]
	v_add_u32_e32 v128, 2, v83
	v_sub_f32_e32 v202, v202, v161
	v_mul_f32_e32 v196, 0x3fb8aa3b, v196
	v_mfma_f32_16x16x32_bf16 v[88:91], v[92:95], v[10:13], v[88:91]
	v_mul_f32_e32 v197, 0x3fb8aa3b, v197
	v_mul_f32_e32 v198, 0x3fb8aa3b, v198
	v_mul_f32_e32 v199, 0x3fb8aa3b, v199
	v_mfma_f32_16x16x32_bf16 v[92:95], v[108:111], v[10:13], v[100:103]
	v_mul_f32_e32 v200, 0x3fb8aa3b, v200
	v_exp_f32_e32 v124, v201
	v_exp_f32_e32 v106, v203
	v_mul_f32_e32 v202, 0x3fb8aa3b, v202
	v_exp_f32_e32 v196, v196
	v_exp_f32_e32 v197, v197
	v_exp_f32_e32 v198, v198
	v_cmp_le_u32_e64 s[4:5], v128, v132
	v_exp_f32_e32 v128, v199
	v_exp_f32_e32 v199, v200
	v_mfma_f32_16x16x32_bf16 v[88:91], v[96:99], v[14:17], v[88:91]
	v_or_b32_e32 v204, 5, v83
	v_add_u32_e32 v205, 7, v83
	v_exp_f32_e32 v125, v202
	v_mfma_f32_16x16x32_bf16 v[92:95], v[112:115], v[14:17], v[92:95]
	v_or_b32_e32 v129, 4, v83
	v_or_b32_e32 v186, 3, v83
	v_cmp_le_u32_e64 s[12:13], v204, v152
	v_cmp_le_u32_e64 s[14:15], v205, v132
	v_or_b32_e32 v187, 6, v83
	v_cmp_gt_u32_e32 vcc, v132, v83
	v_cmp_le_u32_e64 s[6:7], v129, v1
	v_cmp_le_u32_e64 s[8:9], v186, v152
	v_cmp_le_u32_e64 s[16:17], v83, v132
	v_cndmask_b32_e64 v96, 0, v124, s[12:13]
	v_cndmask_b32_e64 v124, 0, v106, s[14:15]
	v_cmp_le_u32_e64 s[10:11], v187, v1
	v_cndmask_b32_e64 v126, 0, v196, s[16:17]
	v_cndmask_b32_e64 v105, 0, v198, s[4:5]
	v_cndmask_b32_e32 v104, 0, v197, vcc
	v_cndmask_b32_e64 v101, 0, v199, s[6:7]
	v_cndmask_b32_e64 v100, 0, v128, s[8:9]
	v_mov_b32_e32 v98, v89
	v_mov_b32_e32 v99, v90
	v_pk_mov_b32 v[90:91], v[90:91], v[92:93] op_sel:[1,0]
	v_mul_f32_e32 v89, v95, v124
	v_cndmask_b32_e64 v97, 0, v125, s[10:11]
	v_mul_f32_e32 v102, v88, v126
	v_mov_b32_e32 v92, v93
	v_mov_b32_e32 v93, v94
	v_pk_mul_f32 v[108:109], v[98:99], v[104:105]
	v_pk_mul_f32 v[110:111], v[90:91], v[100:101]
	v_bfe_u32 v90, v89, 16, 1
	v_pk_mul_f32 v[112:113], v[92:93], v[96:97]
	v_bfe_u32 v91, v102, 16, 1
	v_add3_u32 v89, v89, v90, s53
	v_bfe_u32 v90, v111, 16, 1
	v_bfe_u32 v96, v109, 16, 1
	v_bfe_u32 v92, v110, 16, 1
	v_bfe_u32 v93, v112, 16, 1
	v_bfe_u32 v94, v108, 16, 1
	v_bfe_u32 v97, v113, 16, 1
	v_add3_u32 v91, v102, v91, s53
	v_add3_u32 v96, v109, v96, s53
	v_add3_u32 v90, v111, v90, s53
	v_add3_u32 v94, v108, v94, s53
	v_add3_u32 v98, v112, v93, s53
	v_add3_u32 v92, v110, v92, s53
	v_add3_u32 v93, v113, v97, s53
	v_lshrrev_b32_e32 v91, 16, v91
	v_lshrrev_b32_e32 v97, 16, v90
	v_lshrrev_b32_e32 v96, 16, v96
	v_and_or_b32 v90, v94, s52, v91
	v_and_or_b32 v91, v92, s52, v96
	v_and_or_b32 v92, v98, s52, v97
	ds_read_b128 v[96:99], v206 offset:8704
	ds_read_b128 v[100:103], v206 offset:17408
	v_lshrrev_b32_e32 v93, 16, v93
	v_add_u32_e32 v207, 0, v86
	v_and_or_b32 v93, v89, s52, v93
	v_add_u32_e32 v208, 0, v87
	v_fmac_f32_e32 v185, v88, v126
	s_waitcnt lgkmcnt(1)
	v_mfma_f32_16x16x32_bf16 v[70:73], v[96:99], v[90:93], v[70:73]
	ds_read_b128 v[96:99], v207
	ds_read_b128 v[104:107], v208
	v_add_f32_e32 v88, v108, v185
	v_add_f32_e32 v88, v109, v88
	s_waitcnt lgkmcnt(1)
	v_mfma_f32_16x16x32_bf16 v[66:69], v[96:99], v[90:93], v[66:69]
	ds_read_b128 v[96:99], v206 offset:21760
	v_add_f32_e32 v88, v110, v88
	v_add_f32_e32 v88, v88, v111
	v_mfma_f32_16x16x32_bf16 v[62:65], v[100:103], v[90:93], v[62:65]
	ds_read_b128 v[100:103], v206 offset:26112
	v_add_f32_e32 v88, v112, v88
	s_add_i32 s41, s41, -1
	v_mfma_f32_16x16x32_bf16 v[78:81], v[116:119], v[90:93], v[78:81]
	v_add_f32_e32 v185, v113, v88
	v_add_u32_e32 v87, 64, v87
	v_add_u32_e32 v86, 64, v86
	v_mfma_f32_16x16x32_bf16 v[74:77], v[120:123], v[90:93], v[74:77]
	v_add_u32_e32 v85, 64, v85
	v_add_u32_e32 v84, 0x2200, v84
	v_add_u32_e32 v82, 0x80, v82
	s_waitcnt lgkmcnt(1)
	v_mfma_f32_16x16x32_bf16 v[58:61], v[96:99], v[90:93], v[58:61]
	s_cmp_lg_u32 s41, 0
	v_add_u32_e32 v83, 32, v83
	v_fmac_f32_e32 v185, v95, v124
	s_waitcnt lgkmcnt(0)
	v_mfma_f32_16x16x32_bf16 v[54:57], v[100:103], v[90:93], v[54:57]
	v_mfma_f32_16x16x32_bf16 v[50:53], v[104:107], v[90:93], v[50:53]
	s_cbranch_scc1 .LBB0_1079
; #define LAS __attribute__((address_space(3)))
; __device__ __forceinline__ unsigned pk2(float lo, float hi) { return f2bf(lo) | (f2bf(hi) << 16); }
; __device__ __forceinline__ float bf_lo(unsigned w) { return __uint_as_float(w << 16); }
; __device__ __forceinline__ float bf_hi(unsigned w) { return __uint_as_float(w & 0xffff0000u); }
; __device__ __forceinline__ float sigmoidf_(float x) { return __builtin_amdgcn_rcpf(1.f + __expf(-x)); }
; __device__ __forceinline__ void phase5(const Args& a, LAS unsigned char* lds, int tid, int wave, int lane, int vcu, int G, int pmode) {
;     ...
;         nq += __shfl_xor(nq, 16); nq += __shfl_xor(nq, 32);
;         dsum += __shfl_xor(dsum, 16); dsum += __shfl_xor(dsum, 32);
;         const float den = dsum + aint * nq, inv = 1.f / fmaxf(fabsf(den), __expf(-m_t));
;         float ssq = 0.f;
;         LAS unsigned char* LO = lds + 104960 + wave * (16 * 264);
; #pragma unroll
;         for (int d = 0; d < ((pmode & 8) ? 0 : 8); ++d) {
;             const f32x4 hv = (an[d] + ac[d] * aint) * inv;
;             float h0 = hv[0], h1 = hv[1], h2 = hv[2], h3 = hv[3];
;             if (!(pmode & 16)) { h0 *= sigmoidf_(bf_lo(mo[d].x)); h1 *= sigmoidf_(bf_hi(mo[d].x)); h2 *= sigmoidf_(bf_lo(mo[d].y)); h3 *= sigmoidf_(bf_hi(mo[d].y)); }
;             ssq += (h0 * h0 + h1 * h1) + (h2 * h2 + h3 * h3);
;             u32x2 o; o.x = pk2(h0, h1); o.y = pk2(h2, h3); *(LAS u32x2*)(LO + i16 * 264 + (16 * d + 4 * g) * 2) = o;
;         }
	ds_bpermute_b32 v4, v139, v184
	ds_bpermute_b32 v5, v139, v185
	v_sub_f32_e32 v2, v134, v161
	v_sub_f32_e32 v3, v159, v195
	v_mul_f32_e32 v2, 0x3fb8aa3b, v2
	v_add_f32_e32 v3, v161, v3
	s_waitcnt lgkmcnt(0)
	v_pk_add_f32 v[4:5], v[184:185], v[4:5]
	ds_bpermute_b32 v6, v147, v4
	ds_bpermute_b32 v7, v147, v5
	v_exp_f32_e32 v2, v2
	v_mul_f32_e32 v3, 0xbfb8aa3b, v3
	v_exp_f32_e32 v3, v3
	s_waitcnt lgkmcnt(0)
	v_pk_add_f32 v[4:5], v[4:5], v[6:7]
	s_nop 0
	v_fmac_f32_e32 v5, v2, v4
	v_max_f32_e64 v3, |v5|, v3
	v_div_scale_f32 v4, s[4:5], v3, v3, 1.0
	v_rcp_f32_e32 v5, v4
	s_add_u32 s4, s42, s45
	s_addc_u32 s5, s43, 0
	v_fma_f32 v6, -v4, v5, 1.0
	v_fmac_f32_e32 v5, v6, v5
	v_div_scale_f32 v6, vcc, 1.0, v3, 1.0
	v_mul_f32_e32 v7, v6, v5
	v_fma_f32 v8, -v4, v7, v6
	v_fmac_f32_e32 v7, v8, v5
	v_fma_f32 v4, -v4, v7, v6
	v_div_fmas_f32 v4, v4, v5, v7
	v_lshlrev_b32_e32 v5, 16, v182
	v_mul_f32_e32 v5, 0xbfb8aa3b, v5
	v_and_b32_e32 v6, 0xffff0000, v182
	v_exp_f32_e32 v5, v5
	v_mul_f32_e32 v6, 0xbfb8aa3b, v6
	v_exp_f32_e32 v7, v6
	v_div_fixup_f32 v6, v4, v3, 1.0
	v_add_f32_e32 v3, 1.0, v5
	v_lshlrev_b32_e32 v5, 16, v183
	v_rcp_f32_e32 v4, v3
	v_add_f32_e32 v3, 1.0, v7
	v_mul_f32_e32 v5, 0xbfb8aa3b, v5
	v_and_b32_e32 v7, 0xffff0000, v183
	v_exp_f32_e32 v5, v5
	v_mul_f32_e32 v7, 0xbfb8aa3b, v7
	v_exp_f32_e32 v7, v7
	v_rcp_f32_e32 v8, v3
	v_add_f32_e32 v3, 1.0, v5
	v_rcp_f32_e32 v5, v3
	v_add_f32_e32 v3, 1.0, v7
	v_rcp_f32_e32 v9, v3
	v_pk_fma_f32 v[10:11], v[2:3], v[48:49], v[80:81] op_sel_hi:[0,1,1]
	v_pk_fma_f32 v[12:13], v[2:3], v[46:47], v[78:79] op_sel_hi:[0,1,1]
	v_pk_mul_f32 v[12:13], v[12:13], v[6:7] op_sel_hi:[1,0]
	v_pk_mul_f32 v[10:11], v[10:11], v[6:7] op_sel_hi:[1,0]
	v_mov_b32_e32 v14, v13
	v_mov_b32_e32 v15, v11
	v_mov_b32_e32 v13, v10
	v_pk_mul_f32 v[8:9], v[8:9], v[14:15]
	v_pk_mul_f32 v[10:11], v[4:5], v[12:13]
	v_pk_mul_f32 v[4:5], v[8:9], v[8:9]
	v_and_b32_sdwa v7, v10, v194 dst_sel:DWORD dst_unused:UNUSED_PAD src0_sel:WORD_1 src1_sel:DWORD
	v_pk_fma_f32 v[4:5], v[10:11], v[10:11], v[4:5]
	v_add3_u32 v7, v10, v7, s53
	v_and_b32_sdwa v10, v9, v194 dst_sel:DWORD dst_unused:UNUSED_PAD src0_sel:WORD_1 src1_sel:DWORD
	v_and_b32_sdwa v3, v11, v194 dst_sel:DWORD dst_unused:UNUSED_PAD src0_sel:WORD_1 src1_sel:DWORD
	v_add3_u32 v9, v9, v10, s53
	v_add3_u32 v3, v11, v3, s53
	v_and_b32_sdwa v11, v8, v194 dst_sel:DWORD dst_unused:UNUSED_PAD src0_sel:WORD_1 src1_sel:DWORD
	v_and_b32_e32 v9, 0xffff0000, v9
	v_add3_u32 v8, v8, v11, s53
	v_or_b32_sdwa v11, v9, v3 dst_sel:DWORD dst_unused:UNUSED_PAD src0_sel:DWORD src1_sel:WORD_1
	v_lshlrev_b32_e32 v3, 16, v180
	v_mul_f32_e32 v3, 0xbfb8aa3b, v3
	v_and_b32_e32 v9, 0xffff0000, v180
	v_exp_f32_e32 v3, v3
	v_mul_f32_e32 v9, 0xbfb8aa3b, v9
	v_exp_f32_e32 v9, v9
	v_and_b32_e32 v8, 0xffff0000, v8
	v_or_b32_sdwa v10, v8, v7 dst_sel:DWORD dst_unused:UNUSED_PAD src0_sel:DWORD src1_sel:WORD_1
	v_add_f32_e32 v3, 1.0, v3
	v_lshlrev_b32_e32 v7, 16, v181
	v_rcp_f32_e32 v8, v3
	v_add_f32_e32 v3, 1.0, v9
	v_mul_f32_e32 v7, 0xbfb8aa3b, v7
	v_and_b32_e32 v9, 0xffff0000, v181
	v_exp_f32_e32 v7, v7
	v_mul_f32_e32 v9, 0xbfb8aa3b, v9
	v_exp_f32_e32 v13, v9
	v_rcp_f32_e32 v12, v3
	v_add_f32_e32 v3, 1.0, v7
	v_rcp_f32_e32 v9, v3
	v_add_f32_e32 v3, 1.0, v13
	v_rcp_f32_e32 v13, v3
	v_pk_fma_f32 v[14:15], v[2:3], v[44:45], v[76:77] op_sel_hi:[0,1,1]
	v_pk_fma_f32 v[16:17], v[2:3], v[42:43], v[74:75] op_sel_hi:[0,1,1]
	v_pk_mul_f32 v[16:17], v[16:17], v[6:7] op_sel_hi:[1,0]
	v_pk_mul_f32 v[14:15], v[14:15], v[6:7] op_sel_hi:[1,0]
	v_mov_b32_e32 v42, v17
	v_mov_b32_e32 v43, v15
	v_mov_b32_e32 v17, v14
	v_pk_mul_f32 v[12:13], v[12:13], v[42:43]
	v_pk_mul_f32 v[14:15], v[8:9], v[16:17]
	v_pk_mul_f32 v[8:9], v[12:13], v[12:13]
	v_and_b32_sdwa v7, v14, v194 dst_sel:DWORD dst_unused:UNUSED_PAD src0_sel:WORD_1 src1_sel:DWORD
	v_pk_fma_f32 v[8:9], v[14:15], v[14:15], v[8:9]
	v_and_b32_sdwa v3, v15, v194 dst_sel:DWORD dst_unused:UNUSED_PAD src0_sel:WORD_1 src1_sel:DWORD
	v_add3_u32 v7, v14, v7, s53
	v_and_b32_sdwa v14, v13, v194 dst_sel:DWORD dst_unused:UNUSED_PAD src0_sel:WORD_1 src1_sel:DWORD
	v_add3_u32 v3, v15, v3, s53
	v_and_b32_sdwa v15, v12, v194 dst_sel:DWORD dst_unused:UNUSED_PAD src0_sel:WORD_1 src1_sel:DWORD
	v_add3_u32 v13, v13, v14, s53
	v_add3_u32 v12, v12, v15, s53
	v_and_b32_e32 v13, 0xffff0000, v13
	v_and_b32_e32 v12, 0xffff0000, v12
	v_or_b32_sdwa v13, v13, v3 dst_sel:DWORD dst_unused:UNUSED_PAD src0_sel:DWORD src1_sel:WORD_1
	v_lshlrev_b32_e32 v3, 16, v178
	v_or_b32_sdwa v12, v12, v7 dst_sel:DWORD dst_unused:UNUSED_PAD src0_sel:DWORD src1_sel:WORD_1
	v_mul_f32_e32 v3, 0xbfb8aa3b, v3
	v_and_b32_e32 v7, 0xffff0000, v178
	v_exp_f32_e32 v3, v3
	v_mul_f32_e32 v7, 0xbfb8aa3b, v7
	v_exp_f32_e32 v7, v7
	ds_write2_b64 v192, v[10:11], v[12:13] offset1:4
	v_add_f32_e32 v3, 1.0, v3
	v_rcp_f32_e32 v10, v3
	v_add_f32_e32 v3, 1.0, v7
	v_lshlrev_b32_e32 v7, 16, v179
	v_mul_f32_e32 v7, 0xbfb8aa3b, v7
	v_and_b32_e32 v11, 0xffff0000, v179
	v_exp_f32_e32 v7, v7
	v_mul_f32_e32 v11, 0xbfb8aa3b, v11
	v_exp_f32_e32 v13, v11
	v_rcp_f32_e32 v12, v3
	v_add_f32_e32 v3, 1.0, v7
	v_rcp_f32_e32 v11, v3
	v_add_f32_e32 v3, 1.0, v13
	v_rcp_f32_e32 v13, v3
	v_pk_fma_f32 v[14:15], v[2:3], v[40:41], v[72:73] op_sel_hi:[0,1,1]
	v_pk_fma_f32 v[16:17], v[2:3], v[38:39], v[70:71] op_sel_hi:[0,1,1]
	v_pk_mul_f32 v[16:17], v[16:17], v[6:7] op_sel_hi:[1,0]
	v_pk_mul_f32 v[14:15], v[14:15], v[6:7] op_sel_hi:[1,0]
	v_mov_b32_e32 v38, v17
	v_mov_b32_e32 v39, v15
	v_mov_b32_e32 v17, v14
	v_pk_mul_f32 v[12:13], v[12:13], v[38:39]
	v_pk_mul_f32 v[14:15], v[10:11], v[16:17]
	v_pk_mul_f32 v[10:11], v[12:13], v[12:13]
	v_and_b32_sdwa v7, v14, v194 dst_sel:DWORD dst_unused:UNUSED_PAD src0_sel:WORD_1 src1_sel:DWORD
; #define LAS __attribute__((address_space(3)))
; __device__ __forceinline__ unsigned pk2(float lo, float hi) { return f2bf(lo) | (f2bf(hi) << 16); }
; __device__ __forceinline__ float bf_lo(unsigned w) { return __uint_as_float(w << 16); }
; __device__ __forceinline__ float bf_hi(unsigned w) { return __uint_as_float(w & 0xffff0000u); }
; __device__ __forceinline__ float sigmoidf_(float x) { return __builtin_amdgcn_rcpf(1.f + __expf(-x)); }
; __device__ __forceinline__ void phase5(const Args& a, LAS unsigned char* lds, int tid, int wave, int lane, int vcu, int G, int pmode) {
;     ...
; #pragma unroll
;         for (int d = 0; d < ((pmode & 8) ? 0 : 8); ++d) {
;             const f32x4 hv = (an[d] + ac[d] * aint) * inv;
;             float h0 = hv[0], h1 = hv[1], h2 = hv[2], h3 = hv[3];
;             if (!(pmode & 16)) { h0 *= sigmoidf_(bf_lo(mo[d].x)); h1 *= sigmoidf_(bf_hi(mo[d].x)); h2 *= sigmoidf_(bf_lo(mo[d].y)); h3 *= sigmoidf_(bf_hi(mo[d].y)); }
;             ssq += (h0 * h0 + h1 * h1) + (h2 * h2 + h3 * h3);
;             u32x2 o; o.x = pk2(h0, h1); o.y = pk2(h2, h3); *(LAS u32x2*)(LO + i16 * 264 + (16 * d + 4 * g) * 2) = o;
;         }
	v_pk_fma_f32 v[10:11], v[14:15], v[14:15], v[10:11]
	v_add3_u32 v7, v14, v7, s53
	v_and_b32_sdwa v14, v13, v194 dst_sel:DWORD dst_unused:UNUSED_PAD src0_sel:WORD_1 src1_sel:DWORD
	v_and_b32_sdwa v3, v15, v194 dst_sel:DWORD dst_unused:UNUSED_PAD src0_sel:WORD_1 src1_sel:DWORD
	v_add3_u32 v13, v13, v14, s53
	v_add3_u32 v3, v15, v3, s53
	v_and_b32_sdwa v15, v12, v194 dst_sel:DWORD dst_unused:UNUSED_PAD src0_sel:WORD_1 src1_sel:DWORD
	v_and_b32_e32 v13, 0xffff0000, v13
	v_add3_u32 v12, v12, v15, s53
	v_or_b32_sdwa v15, v13, v3 dst_sel:DWORD dst_unused:UNUSED_PAD src0_sel:DWORD src1_sel:WORD_1
	v_lshlrev_b32_e32 v3, 16, v176
	v_mul_f32_e32 v3, 0xbfb8aa3b, v3
	v_and_b32_e32 v13, 0xffff0000, v176
	v_exp_f32_e32 v3, v3
	v_mul_f32_e32 v13, 0xbfb8aa3b, v13
	v_exp_f32_e32 v13, v13
	v_and_b32_e32 v12, 0xffff0000, v12
	v_or_b32_sdwa v14, v12, v7 dst_sel:DWORD dst_unused:UNUSED_PAD src0_sel:DWORD src1_sel:WORD_1
	v_add_f32_e32 v3, 1.0, v3
	v_lshlrev_b32_e32 v7, 16, v177
	v_rcp_f32_e32 v12, v3
	v_add_f32_e32 v3, 1.0, v13
	v_mul_f32_e32 v7, 0xbfb8aa3b, v7
	v_and_b32_e32 v13, 0xffff0000, v177
	v_exp_f32_e32 v7, v7
	v_mul_f32_e32 v13, 0xbfb8aa3b, v13
	v_exp_f32_e32 v17, v13
	v_rcp_f32_e32 v16, v3
	v_add_f32_e32 v3, 1.0, v7
	v_rcp_f32_e32 v13, v3
	v_add_f32_e32 v3, 1.0, v17
	v_rcp_f32_e32 v17, v3
	v_pk_fma_f32 v[36:37], v[2:3], v[36:37], v[68:69] op_sel_hi:[0,1,1]
	v_pk_fma_f32 v[34:35], v[2:3], v[34:35], v[66:67] op_sel_hi:[0,1,1]
	v_pk_mul_f32 v[34:35], v[34:35], v[6:7] op_sel_hi:[1,0]
	v_pk_mul_f32 v[36:37], v[36:37], v[6:7] op_sel_hi:[1,0]
	v_mov_b32_e32 v38, v35
	v_mov_b32_e32 v39, v37
	v_mov_b32_e32 v35, v36
	v_pk_mul_f32 v[16:17], v[16:17], v[38:39]
	v_pk_mul_f32 v[34:35], v[12:13], v[34:35]
	v_pk_mul_f32 v[12:13], v[16:17], v[16:17]
	v_and_b32_sdwa v7, v34, v194 dst_sel:DWORD dst_unused:UNUSED_PAD src0_sel:WORD_1 src1_sel:DWORD
	v_pk_fma_f32 v[12:13], v[34:35], v[34:35], v[12:13]
	v_and_b32_sdwa v3, v35, v194 dst_sel:DWORD dst_unused:UNUSED_PAD src0_sel:WORD_1 src1_sel:DWORD
	v_add3_u32 v7, v34, v7, s53
	v_and_b32_sdwa v34, v17, v194 dst_sel:DWORD dst_unused:UNUSED_PAD src0_sel:WORD_1 src1_sel:DWORD
	v_add3_u32 v3, v35, v3, s53
	v_and_b32_sdwa v35, v16, v194 dst_sel:DWORD dst_unused:UNUSED_PAD src0_sel:WORD_1 src1_sel:DWORD
	v_add3_u32 v17, v17, v34, s53
	v_add3_u32 v16, v16, v35, s53
	v_and_b32_e32 v17, 0xffff0000, v17
	v_and_b32_e32 v16, 0xffff0000, v16
	v_or_b32_sdwa v17, v17, v3 dst_sel:DWORD dst_unused:UNUSED_PAD src0_sel:DWORD src1_sel:WORD_1
	v_lshlrev_b32_e32 v3, 16, v174
	v_or_b32_sdwa v16, v16, v7 dst_sel:DWORD dst_unused:UNUSED_PAD src0_sel:DWORD src1_sel:WORD_1
	v_mul_f32_e32 v3, 0xbfb8aa3b, v3
	v_and_b32_e32 v7, 0xffff0000, v174
	v_exp_f32_e32 v3, v3
	v_mul_f32_e32 v7, 0xbfb8aa3b, v7
	v_exp_f32_e32 v7, v7
	ds_write2_b64 v192, v[14:15], v[16:17] offset0:8 offset1:12
	v_add_f32_e32 v3, 1.0, v3
	v_rcp_f32_e32 v14, v3
	v_add_f32_e32 v3, 1.0, v7
	v_lshlrev_b32_e32 v7, 16, v175
	v_mul_f32_e32 v7, 0xbfb8aa3b, v7
	v_and_b32_e32 v15, 0xffff0000, v175
	v_exp_f32_e32 v7, v7
	v_mul_f32_e32 v15, 0xbfb8aa3b, v15
	v_exp_f32_e32 v17, v15
	v_rcp_f32_e32 v16, v3
	v_add_f32_e32 v3, 1.0, v7
	v_rcp_f32_e32 v15, v3
	v_add_f32_e32 v3, 1.0, v17
	v_rcp_f32_e32 v17, v3
	v_pk_fma_f32 v[32:33], v[2:3], v[32:33], v[64:65] op_sel_hi:[0,1,1]
	v_pk_fma_f32 v[30:31], v[2:3], v[30:31], v[62:63] op_sel_hi:[0,1,1]
	v_pk_mul_f32 v[30:31], v[30:31], v[6:7] op_sel_hi:[1,0]
	v_pk_mul_f32 v[32:33], v[32:33], v[6:7] op_sel_hi:[1,0]
	v_mov_b32_e32 v34, v31
	v_mov_b32_e32 v35, v33
	v_mov_b32_e32 v31, v32
	v_pk_mul_f32 v[16:17], v[16:17], v[34:35]
	v_pk_mul_f32 v[14:15], v[14:15], v[30:31]
	v_pk_mul_f32 v[30:31], v[16:17], v[16:17]
	v_and_b32_sdwa v7, v14, v194 dst_sel:DWORD dst_unused:UNUSED_PAD src0_sel:WORD_1 src1_sel:DWORD
	v_pk_fma_f32 v[30:31], v[14:15], v[14:15], v[30:31]
	v_and_b32_sdwa v3, v15, v194 dst_sel:DWORD dst_unused:UNUSED_PAD src0_sel:WORD_1 src1_sel:DWORD
	v_add3_u32 v7, v14, v7, s53
	v_and_b32_sdwa v14, v17, v194 dst_sel:DWORD dst_unused:UNUSED_PAD src0_sel:WORD_1 src1_sel:DWORD
	v_add3_u32 v3, v15, v3, s53
	v_and_b32_sdwa v15, v16, v194 dst_sel:DWORD dst_unused:UNUSED_PAD src0_sel:WORD_1 src1_sel:DWORD
	v_add3_u32 v14, v17, v14, s53
	v_add3_u32 v15, v16, v15, s53
	v_and_b32_e32 v14, 0xffff0000, v14
	v_and_b32_e32 v16, 0xffff0000, v15
	v_or_b32_sdwa v15, v14, v3 dst_sel:DWORD dst_unused:UNUSED_PAD src0_sel:DWORD src1_sel:WORD_1
	v_lshlrev_b32_e32 v3, 16, v172
	v_mul_f32_e32 v3, 0xbfb8aa3b, v3
	v_and_b32_e32 v14, 0xffff0000, v172
	v_exp_f32_e32 v3, v3
	v_mul_f32_e32 v14, 0xbfb8aa3b, v14
	v_exp_f32_e32 v17, v14
	v_or_b32_sdwa v14, v16, v7 dst_sel:DWORD dst_unused:UNUSED_PAD src0_sel:DWORD src1_sel:WORD_1
	v_add_f32_e32 v3, 1.0, v3
	v_lshlrev_b32_e32 v7, 16, v173
	v_rcp_f32_e32 v16, v3
	v_add_f32_e32 v3, 1.0, v17
	v_mul_f32_e32 v7, 0xbfb8aa3b, v7
	v_and_b32_e32 v17, 0xffff0000, v173
	v_exp_f32_e32 v7, v7
	v_mul_f32_e32 v17, 0xbfb8aa3b, v17
	v_exp_f32_e32 v33, v17
	v_rcp_f32_e32 v32, v3
	v_add_f32_e32 v3, 1.0, v7
	v_rcp_f32_e32 v17, v3
	v_add_f32_e32 v3, 1.0, v33
	v_rcp_f32_e32 v33, v3
	v_pk_fma_f32 v[28:29], v[2:3], v[28:29], v[60:61] op_sel_hi:[0,1,1]
	v_pk_fma_f32 v[26:27], v[2:3], v[26:27], v[58:59] op_sel_hi:[0,1,1]
	v_pk_mul_f32 v[26:27], v[26:27], v[6:7] op_sel_hi:[1,0]
	v_pk_mul_f32 v[28:29], v[28:29], v[6:7] op_sel_hi:[1,0]
	v_mov_b32_e32 v34, v27
	v_mov_b32_e32 v35, v29
	v_mov_b32_e32 v27, v28
	v_pk_mul_f32 v[32:33], v[32:33], v[34:35]
	v_pk_mul_f32 v[16:17], v[16:17], v[26:27]
	v_pk_mul_f32 v[26:27], v[32:33], v[32:33]
	v_and_b32_sdwa v7, v16, v194 dst_sel:DWORD dst_unused:UNUSED_PAD src0_sel:WORD_1 src1_sel:DWORD
	v_pk_fma_f32 v[26:27], v[16:17], v[16:17], v[26:27]
; #define LAS __attribute__((address_space(3)))
; __device__ __forceinline__ unsigned pk2(float lo, float hi) { return f2bf(lo) | (f2bf(hi) << 16); }
; __device__ __forceinline__ float bf_lo(unsigned w) { return __uint_as_float(w << 16); }
; __device__ __forceinline__ float bf_hi(unsigned w) { return __uint_as_float(w & 0xffff0000u); }
; __device__ __forceinline__ float sigmoidf_(float x) { return __builtin_amdgcn_rcpf(1.f + __expf(-x)); }
; __device__ __forceinline__ void phase5(const Args& a, LAS unsigned char* lds, int tid, int wave, int lane, int vcu, int G, int pmode) {
;     ...
; #pragma unroll
;         for (int d = 0; d < ((pmode & 8) ? 0 : 8); ++d) {
;             const f32x4 hv = (an[d] + ac[d] * aint) * inv;
;             float h0 = hv[0], h1 = hv[1], h2 = hv[2], h3 = hv[3];
;             if (!(pmode & 16)) { h0 *= sigmoidf_(bf_lo(mo[d].x)); h1 *= sigmoidf_(bf_hi(mo[d].x)); h2 *= sigmoidf_(bf_lo(mo[d].y)); h3 *= sigmoidf_(bf_hi(mo[d].y)); }
;             ssq += (h0 * h0 + h1 * h1) + (h2 * h2 + h3 * h3);
;             u32x2 o; o.x = pk2(h0, h1); o.y = pk2(h2, h3); *(LAS u32x2*)(LO + i16 * 264 + (16 * d + 4 * g) * 2) = o;
;         }
;         if (!(pmode & 40)) {
; #pragma unroll
;             for (int j = 0; j < 4; ++j) { const int tk = (lane >> 4) + 4 * j, ch = lane & 15;
;                 const u32x2 lo2 = *(const LAS u32x2*)(LO + tk * 264 + 16 * ch), hi2 = *(const LAS u32x2*)(LO + tk * 264 + 16 * ch + 8);
;                 u32x4 w; w.x = lo2.x; w.y = lo2.y; w.z = hi2.x; w.w = hi2.y;
;                 *(u32x4*)(HM + ((size_t)128 * c + 16 * tg + tk) * 512 + hd * 128 + 8 * ch) = w; }
;         }
;         ssq += __shfl_xor(ssq, 16); ssq += __shfl_xor(ssq, 32);
;         if (g == 0) SSM[t * 4 + hd] = ssq;
;     }
	v_and_b32_sdwa v3, v17, v194 dst_sel:DWORD dst_unused:UNUSED_PAD src0_sel:WORD_1 src1_sel:DWORD
	v_add3_u32 v7, v16, v7, s53
	v_and_b32_sdwa v16, v33, v194 dst_sel:DWORD dst_unused:UNUSED_PAD src0_sel:WORD_1 src1_sel:DWORD
	v_add3_u32 v3, v17, v3, s53
	v_and_b32_sdwa v17, v32, v194 dst_sel:DWORD dst_unused:UNUSED_PAD src0_sel:WORD_1 src1_sel:DWORD
	v_add3_u32 v16, v33, v16, s53
	v_add3_u32 v17, v32, v17, s53
	v_and_b32_e32 v16, 0xffff0000, v16
	v_and_b32_e32 v28, 0xffff0000, v17
	v_or_b32_sdwa v17, v16, v3 dst_sel:DWORD dst_unused:UNUSED_PAD src0_sel:DWORD src1_sel:WORD_1
	v_lshlrev_b32_e32 v3, 16, v170
	v_or_b32_sdwa v16, v28, v7 dst_sel:DWORD dst_unused:UNUSED_PAD src0_sel:DWORD src1_sel:WORD_1
	v_mul_f32_e32 v3, 0xbfb8aa3b, v3
	v_and_b32_e32 v7, 0xffff0000, v170
	v_exp_f32_e32 v3, v3
	v_mul_f32_e32 v7, 0xbfb8aa3b, v7
	v_exp_f32_e32 v7, v7
	ds_write2_b64 v192, v[14:15], v[16:17] offset0:16 offset1:20
	v_add_f32_e32 v3, 1.0, v3
	v_rcp_f32_e32 v14, v3
	v_add_f32_e32 v3, 1.0, v7
	v_lshlrev_b32_e32 v7, 16, v171
	v_mul_f32_e32 v7, 0xbfb8aa3b, v7
	v_and_b32_e32 v15, 0xffff0000, v171
	v_exp_f32_e32 v7, v7
	v_mul_f32_e32 v15, 0xbfb8aa3b, v15
	v_exp_f32_e32 v17, v15
	v_rcp_f32_e32 v16, v3
	v_add_f32_e32 v3, 1.0, v7
	v_rcp_f32_e32 v15, v3
	v_add_f32_e32 v3, 1.0, v17
	v_rcp_f32_e32 v17, v3
	v_pk_fma_f32 v[24:25], v[2:3], v[24:25], v[56:57] op_sel_hi:[0,1,1]
	v_pk_fma_f32 v[22:23], v[2:3], v[22:23], v[54:55] op_sel_hi:[0,1,1]
	v_pk_mul_f32 v[22:23], v[22:23], v[6:7] op_sel_hi:[1,0]
	v_pk_mul_f32 v[24:25], v[24:25], v[6:7] op_sel_hi:[1,0]
	v_mov_b32_e32 v28, v23
	v_mov_b32_e32 v29, v25
	v_mov_b32_e32 v23, v24
	v_pk_mul_f32 v[16:17], v[16:17], v[28:29]
	v_pk_mul_f32 v[14:15], v[14:15], v[22:23]
	v_pk_mul_f32 v[22:23], v[16:17], v[16:17]
	v_and_b32_sdwa v7, v14, v194 dst_sel:DWORD dst_unused:UNUSED_PAD src0_sel:WORD_1 src1_sel:DWORD
	v_pk_fma_f32 v[22:23], v[14:15], v[14:15], v[22:23]
	v_and_b32_sdwa v3, v15, v194 dst_sel:DWORD dst_unused:UNUSED_PAD src0_sel:WORD_1 src1_sel:DWORD
	v_add3_u32 v7, v14, v7, s53
	v_and_b32_sdwa v14, v17, v194 dst_sel:DWORD dst_unused:UNUSED_PAD src0_sel:WORD_1 src1_sel:DWORD
	v_add3_u32 v3, v15, v3, s53
	v_and_b32_sdwa v15, v16, v194 dst_sel:DWORD dst_unused:UNUSED_PAD src0_sel:WORD_1 src1_sel:DWORD
	v_add3_u32 v14, v17, v14, s53
	v_add3_u32 v15, v16, v15, s53
	v_and_b32_e32 v14, 0xffff0000, v14
	v_and_b32_e32 v16, 0xffff0000, v15
	v_or_b32_sdwa v15, v14, v3 dst_sel:DWORD dst_unused:UNUSED_PAD src0_sel:DWORD src1_sel:WORD_1
	v_lshlrev_b32_e32 v3, 16, v164
	v_mul_f32_e32 v3, 0xbfb8aa3b, v3
	v_and_b32_e32 v14, 0xffff0000, v164
	v_exp_f32_e32 v3, v3
	v_mul_f32_e32 v14, 0xbfb8aa3b, v14
	v_exp_f32_e32 v17, v14
	v_or_b32_sdwa v14, v16, v7 dst_sel:DWORD dst_unused:UNUSED_PAD src0_sel:DWORD src1_sel:WORD_1
	v_add_f32_e32 v3, 1.0, v3
	v_lshlrev_b32_e32 v7, 16, v165
	v_rcp_f32_e32 v16, v3
	v_add_f32_e32 v3, 1.0, v17
	v_mul_f32_e32 v7, 0xbfb8aa3b, v7
	v_and_b32_e32 v17, 0xffff0000, v165
	v_exp_f32_e32 v7, v7
	v_mul_f32_e32 v17, 0xbfb8aa3b, v17
	v_exp_f32_e32 v25, v17
	v_rcp_f32_e32 v24, v3
	v_add_f32_e32 v3, 1.0, v7
	v_rcp_f32_e32 v17, v3
	v_add_f32_e32 v3, 1.0, v25
	v_rcp_f32_e32 v25, v3
	v_pk_fma_f32 v[20:21], v[2:3], v[20:21], v[52:53] op_sel_hi:[0,1,1]
	v_pk_fma_f32 v[2:3], v[2:3], v[18:19], v[50:51] op_sel_hi:[0,1,1]
	v_pk_mul_f32 v[2:3], v[2:3], v[6:7] op_sel_hi:[1,0]
	v_pk_mul_f32 v[6:7], v[20:21], v[6:7] op_sel_hi:[1,0]
	v_mov_b32_e32 v18, v3
	v_mov_b32_e32 v19, v7
	v_mov_b32_e32 v3, v6
	v_pk_mul_f32 v[18:19], v[24:25], v[18:19]
	v_pk_mul_f32 v[2:3], v[16:17], v[2:3]
	v_pk_mul_f32 v[6:7], v[18:19], v[18:19]
	v_and_b32_sdwa v16, v3, v194 dst_sel:DWORD dst_unused:UNUSED_PAD src0_sel:WORD_1 src1_sel:DWORD
	v_and_b32_sdwa v17, v2, v194 dst_sel:DWORD dst_unused:UNUSED_PAD src0_sel:WORD_1 src1_sel:DWORD
	v_pk_fma_f32 v[6:7], v[2:3], v[2:3], v[6:7]
	v_add3_u32 v2, v2, v17, s53
	v_add3_u32 v3, v3, v16, s53
	v_and_b32_sdwa v16, v19, v194 dst_sel:DWORD dst_unused:UNUSED_PAD src0_sel:WORD_1 src1_sel:DWORD
	v_and_b32_sdwa v17, v18, v194 dst_sel:DWORD dst_unused:UNUSED_PAD src0_sel:WORD_1 src1_sel:DWORD
	v_add3_u32 v16, v19, v16, s53
	v_add3_u32 v17, v18, v17, s53
	v_and_b32_e32 v16, 0xffff0000, v16
	v_and_b32_e32 v17, 0xffff0000, v17
	v_or_b32_sdwa v3, v16, v3 dst_sel:DWORD dst_unused:UNUSED_PAD src0_sel:DWORD src1_sel:WORD_1
	v_or_b32_sdwa v2, v17, v2 dst_sel:DWORD dst_unused:UNUSED_PAD src0_sel:DWORD src1_sel:WORD_1
	ds_write2_b64 v192, v[14:15], v[2:3] offset0:24 offset1:28
	ds_read2_b64 v[14:17], v193 offset1:1
	ds_read2_b64 v[18:21], v193 offset0:132 offset1:133
	v_add_f32_e32 v8, v8, v9
	v_add_f32_e32 v4, v4, v5
	v_mov_b32_e32 v3, s5
	v_or_b32_e32 v2, s4, v130
	v_add_f32_e32 v4, v4, v8
	v_add_f32_e32 v5, v10, v11
	v_lshl_add_u64 v[24:25], v[140:141], 0, s[30:31]
	v_lshlrev_b64 v[2:3], 10, v[2:3]
	v_add_f32_e32 v4, v5, v4
	v_add_f32_e32 v5, v12, v13
	v_lshl_add_u64 v[2:3], v[24:25], 0, v[2:3]
	v_add_f32_e32 v4, v5, v4
	v_add_f32_e32 v5, v30, v31
	s_waitcnt lgkmcnt(1)
	global_store_dwordx4 v[2:3], v[14:17], off
	v_mov_b32_e32 v3, s5
	v_or_b32_e32 v2, s4, v146
	v_add_f32_e32 v4, v5, v4
	v_add_f32_e32 v5, v26, v27
	v_lshlrev_b64 v[2:3], 10, v[2:3]
	v_add_f32_e32 v4, v5, v4
	v_add_f32_e32 v5, v22, v23
	v_lshl_add_u64 v[2:3], v[24:25], 0, v[2:3]
	v_add_f32_e32 v4, v5, v4
	v_add_f32_e32 v5, v6, v7
	s_waitcnt lgkmcnt(0)
	global_store_dwordx4 v[2:3], v[18:21], off
	v_add_u32_e32 v2, 0x840, v193
	v_add_f32_e32 v8, v5, v4
	ds_read2_b64 v[14:17], v2 offset1:1
	ds_bpermute_b32 v10, v139, v8
	v_add_u32_e32 v4, 0xc60, v193
	v_mov_b32_e32 v3, s5
	ds_read2_b64 v[4:7], v4 offset1:1
	v_or_b32_e32 v2, s4, v148
	v_lshlrev_b64 v[2:3], 10, v[2:3]
	v_lshl_add_u64 v[2:3], v[24:25], 0, v[2:3]
	s_waitcnt lgkmcnt(2)
	global_store_dwordx4 v[2:3], v[14:17], off
	s_waitcnt lgkmcnt(1)
	v_add_f32_e32 v2, v8, v10
	ds_bpermute_b32 v3, v147, v2
	v_mov_b32_e32 v9, s5
	v_or_b32_e32 v8, s4, v150
	v_lshlrev_b64 v[8:9], 10, v[8:9]
	v_lshl_add_u64 v[8:9], v[24:25], 0, v[8:9]
	s_waitcnt lgkmcnt(1)
	global_store_dwordx4 v[8:9], v[4:7], off
	s_and_saveexec_b64 s[4:5], s[2:3]
	s_cbranch_execz .LBB0_1063
	s_waitcnt lgkmcnt(0)
	v_add_f32_e32 v4, v2, v3
	v_lshl_add_u64 v[2:3], v[162:163], 2, s[28:29]
	global_store_dword v[2:3], v4, off
	s_branch .LBB0_1063

; #define PG8_BAR __builtin_amdgcn_s_barrier()
; template <class Epi, class Sched, bool ALIGN_EPI = false, bool SP2 = false>
; __device__ __forceinline__ void gemm_phase(PG8_LAS unsigned char* lds, const Gemm g, const Sched& S, const Epi& E) {
;     const int tid = threadIdx.x, wid = __builtin_amdgcn_readfirstlane(tid >> 6), lane = tid & 63, wr = wid >> 2, wc = wid & 3, fr = lane & 15, fq = lane >> 4;
;     const int K = g.K, nt = K / BK;
;     unsigned voffA[2], voffB[2];
; #pragma unroll
;     for (int i = 0; i < 2; ++i) { int R, C; stage_rc(tid * 16 + i * 8192, R, C); const int Rb = Epi::PERM ? ((R & ~31) + perm32(R & 31)) : R;
;         voffA[i] = (unsigned)(R * K + C) * 2u; voffB[i] = (unsigned)(Rb * K + C) * 2u; }
;     const size_t kstep = (size_t)(BK * 2);
;     const size_t hstep = (size_t)HALF * K * 2;
;     const size_t tstep = 2 * hstep;
;     const unsigned ldsw = (unsigned)wid * 1024u;
;     const int aoff = lds_byte(wr * 64 + fr, fq * 8), boff = lds_byte(wc * 32 + fr, fq * 8);
;     ...
;     Unit cur, nxt; int ui = 0;
;     if (!S.next(0, cur)) return;
;     f32x4 acc[2][2][4][2];
; #pragma unroll
;     for (int a = 0; a < 2; ++a)
; #pragma unroll
;         for (int b = 0; b < 2; ++b)
; #pragma unroll
;             for (int m = 0; m < 4; ++m)
; #pragma unroll
;                 for (int n = 0; n < 2; ++n) acc[a][b][m][n] = (f32x4){0.f, 0.f, 0.f, 0.f};
;     bf16x8 At[4][2], B0[2][2], B1[2][2];
;     const char* cA; const char* cB;
;     if constexpr (Epi::PAIR) { cA = (const char*)(cur.half ? g.A2 : g.A) + (size_t)cur.pm * tstep; cB = (const char*)(cur.half ? g.Bt2 : g.Bt) + (size_t)cur.pn * tstep; }
;     else { cA = (const char*)g.A + (size_t)cur.pm * tstep; cB = (const char*)g.Bt + (size_t)cur.pn * tstep; }
;     S.a_ready(cur);
;     if constexpr (SP2) {
;         PG8_STAGE(PG8_SB(0, 0), cB, voffB); PG8_STAGE(PG8_SB(0, 1), cB + hstep, voffB); PG8_STAGE(PG8_SA(0, 0), cA, voffA); PG8_STAGE(PG8_SA(0, 1), cA + hstep, voffA);
;         if (wr == 1) PG8_BAR;
;         PG8_WAIT_V(2); PG8_BAR;
;         PG8_STAGE(PG8_SB(1, 0), cB + kstep, voffB); PG8_STAGE(PG8_SA(1, 0), cA + kstep, voffA); PG8_STAGE(PG8_SB(1, 1), cB + hstep + kstep, voffB);
;         PG8_WAIT_V(6); PG8_BAR;
;     } else {
;         PG8_STAGE(PG8_SB(0, 0), cB, voffB); PG8_STAGE(PG8_SA(0, 0), cA, voffA); PG8_STAGE(PG8_SB(0, 1), cB + hstep, voffB); PG8_STAGE(PG8_SA(0, 1), cA + hstep, voffA);
.LBB0_1132:
	s_or_b64 exec, exec, s[2:3]
	s_waitcnt lgkmcnt(0)
	s_barrier
	s_branch .Lpin_6
	.p2align 8
	s_nop 0
	s_nop 0
	s_nop 0
	s_nop 0
	s_nop 0
	s_nop 0
	s_nop 0
	s_nop 0
	s_nop 0
	s_nop 0
	s_nop 0
	s_nop 0
	s_nop 0
	s_nop 0
	s_nop 0
	s_nop 0
	s_nop 0
	s_nop 0
	s_nop 0
	s_nop 0
	s_nop 0
	s_nop 0
	s_nop 0
	s_nop 0
	s_nop 0
	s_nop 0
	s_nop 0
	s_nop 0
	s_nop 0
	s_nop 0
	s_nop 0
	s_nop 0
	s_nop 0
	s_nop 0
	s_nop 0
	s_nop 0
	s_nop 0
	s_nop 0
	s_nop 0
	s_nop 0
	s_nop 0
	s_nop 0
	s_nop 0
	s_nop 0
	s_nop 0
	s_nop 0
	s_nop 0
	s_nop 0
	s_nop 0
	s_nop 0
	s_nop 0
	s_nop 0
	s_nop 0
	s_nop 0
	s_nop 0
.Lpin_6:
.LBB0_1133:
	s_cmp_lt_i32 s86, 7
	s_cselect_b64 s[6:7], -1, 0
	s_and_b64 s[0:1], s[6:7], s[0:1]
	s_andn2_b64 vcc, exec, s[0:1]
	v_lshlrev_b32_e32 v1, 4, v0
	s_cbranch_vccnz .LBB0_1209
	s_add_u32 s8, s84, 0x12500000
	s_addc_u32 s9, s85, 0
	s_add_u32 s10, s84, 0x1400000
	s_addc_u32 s11, s85, 0
	s_add_u32 s33, s84, 0x22600000
	s_addc_u32 s42, s85, 0
	s_add_u32 s43, s84, 0x1500000
	s_addc_u32 s44, s85, 0
	s_add_u32 s12, s84, 0x23700000
	s_addc_u32 s13, s85, 0
	s_add_u32 s14, s84, 0x23800000
	s_addc_u32 s15, s85, 0
	s_add_u32 s16, s84, 0x15a00000
	s_addc_u32 s17, s85, 0
	v_readlane_b32 s0, v253, 4
	v_and_b32_e32 v167, 15, v0
	s_cmpk_gt_i32 s0, 0xff
	v_readfirstlane_b32 s1, v0
	s_cbranch_scc1 .LBB0_1164
	s_waitcnt vmcnt(0)
	v_lshlrev_b32_e32 v4, 1, v168
	v_lshrrev_b32_e32 v5, 5, v0
	v_and_b32_e32 v2, 32, v0
	v_and_b32_e32 v4, 24, v4
	v_and_b32_e32 v5, 4, v5
	v_and_b32_e32 v6, 3, v168
	v_and_b32_e32 v13, 15, v168
	v_bitop3_b32 v2, v1, v2, 48 bitop3:0x6c
	v_and_b32_e32 v12, 64, v0
	v_or3_b32 v4, v5, v6, v4
	v_lshrrev_b32_e32 v5, 3, v0
	v_or_b32_e32 v3, v2, v12
	v_and_or_b32 v6, v5, 48, v13
	v_and_or_b32 v5, v5, 32, v4
	v_or_b32_e32 v14, 0x2000, v1
	v_lshl_or_b32 v172, v5, 10, v3
	v_lshrrev_b32_e32 v5, 7, v14
	s_movk_i32 s0, 0x70
	v_readlane_b32 s3, v253, 4
	v_lshl_or_b32 v170, v6, 10, v3
	v_and_or_b32 v6, v5, s0, v13
	s_movk_i32 s0, 0x60
	s_ashr_i32 s46, s3, 31
	v_and_or_b32 v4, v5, s0, v4
	s_lshr_b32 s0, s46, 29
	s_add_i32 s0, s3, s0
	s_and_b32 s2, s0, -8
	s_lshr_b32 s20, s1, 6
	s_sub_i32 s2, s3, s2
	s_lshr_b32 s22, s1, 8
	s_lshl_b32 s45, s20, 10
	s_lshl_b32 s4, s2, 5
	s_ashr_i32 s0, s0, 3
	s_mul_i32 s3, s2, 33
	s_cmp_lt_i32 s2, 0
	s_cselect_b32 s2, s3, s4
	s_add_i32 s0, s2, s0
	s_ashr_i32 s2, s0, 31
	s_lshr_b32 s2, s2, 27
	s_add_i32 s2, s0, s2
	s_ashr_i32 s3, s2, 5
	s_andn2_b32 s2, s2, 31
	s_sub_i32 s2, s0, s2
	s_bfe_i32 s0, s2, 0x80000
	s_bfe_u32 s0, s0, 0x3000c
	s_add_i32 s4, s2, s0
	s_bfe_i32 s0, s4, 0x80000
	s_and_b32 s4, s4, 0xf8
	s_sub_i32 s2, s2, s4
	s_lshl_b32 s3, s3, 3
	s_sext_i32_i16 s0, s0
	s_sext_i32_i8 s2, s2
	s_lshr_b32 s0, s0, 3
	s_add_i32 s2, s3, s2
	s_ashr_i32 s3, s2, 31
	s_bfe_i64 s[18:19], s[0:1], 0x100000
	s_lshl_b64 s[4:5], s[2:3], 18
	s_lshl_b64 s[18:19], s[18:19], 18
	s_add_u32 s38, s10, s18
	s_addc_u32 s39, s11, s19
	s_add_i32 s47, s45, 0
	s_add_i32 m0, s47, 0x10000
	v_lshl_or_b32 v176, v4, 10, v3
	global_load_lds_dwordx4 v172, s[38:39]
	s_add_i32 m0, s47, 0x12000
	s_add_u32 s18, s38, 0x20000
	global_load_lds_dwordx4 v176, s[38:39]
	s_addc_u32 s19, s39, 0
	s_add_i32 m0, s47, 0x14000
	v_lshl_or_b32 v174, v6, 10, v3
	global_load_lds_dwordx4 v172, s[18:19]
	s_add_i32 m0, s47, 0x16000
	s_add_u32 s36, s8, s4
	s_addc_u32 s37, s9, s5
	s_add_i32 s48, s47, 0x2000
	global_load_lds_dwordx4 v176, s[18:19]
	s_mov_b32 m0, s47
	s_add_u32 s4, s36, 0x20000
	global_load_lds_dwordx4 v170, s[36:37]
	s_mov_b32 m0, s48
	s_addc_u32 s5, s37, 0
	s_add_i32 s49, s47, 0x4000
	global_load_lds_dwordx4 v174, s[36:37]
	s_mov_b32 m0, s49
	s_add_i32 s50, s47, 0x6000
	global_load_lds_dwordx4 v170, s[4:5]
	s_mov_b32 m0, s50
	v_mov_b32_e32 v3, 0
	global_load_lds_dwordx4 v174, s[4:5]
	v_mov_b32_e32 v173, v3
	v_mov_b32_e32 v177, v3
	v_mov_b32_e32 v171, v3
	v_mov_b32_e32 v175, v3
	s_cmp_eq_u32 s22, 1
	v_lshl_add_u64 v[10:11], s[38:39], 0, v[172:173]
	v_lshl_add_u64 v[8:9], s[38:39], 0, v[176:177]
	v_lshl_add_u64 v[6:7], s[36:37], 0, v[170:171]
	v_lshl_add_u64 v[4:5], s[36:37], 0, v[174:175]
	s_movk_i32 s51, 0x4000
	s_cselect_b64 s[4:5], -1, 0
	s_cmp_lg_u32 s22, 1
	s_movk_i32 s52, 0x6000
	s_cbranch_scc1 .LBB0_1137
	s_barrier

;     __device__ __forceinline__ void mid(pg8::f32x4 (&acc)[2][2][4][2], const pg8::Unit& u, int wr, int wc, int fr, int fq) const {
;         const int row0 = u.pm * 256 + wr * 64 + fr;
; #pragma unroll
;         for (int ai = 0; ai < 2; ++ai)
; #pragma unroll
;             for (int m = 0; m < 4; ++m) {
;                 const int r = row0 + ai * 128 + m * 16;
;                 const f32x4 a0 = *(const f32x4*)(SSA + (size_t)r * 8), a1 = *(const f32x4*)(SSA + (size_t)r * 8 + 4), m0 = *(const f32x4*)(SSM + (size_t)r * 4);
;                 const float ssa = ((a0[0] + a0[1]) + (a0[2] + a0[3])) + ((a1[0] + a1[1]) + (a1[2] + a1[3])), ssm = (m0[0] + m0[1]) + (m0[2] + m0[3]);
;                 const float ratio = __builtin_amdgcn_rsqf(ssa * (1.f / 512.f) + EPS) * __builtin_amdgcn_sqrtf(ssm * (1.f / 512.f) + EPS);
; #pragma unroll
;                 for (int bj = 0; bj < 2; ++bj) { acc[ai][bj][m][0] = acc[ai][bj][m][0] * ratio; acc[ai][bj][m][1] = acc[ai][bj][m][1] * ratio; }
;             }
;     }
.LBB0_1156:
	v_lshl_add_u64 v[134:135], v[4:5], 4, s[14:15]
	global_load_dwordx4 v[138:141], v[134:135], off
	v_lshlrev_b64 v[134:135], 5, v[4:5]
	v_lshlrev_b64 v[154:155], 5, v[152:153]
	v_lshl_add_u64 v[134:135], s[12:13], 0, v[134:135]
	v_lshl_add_u64 v[154:155], s[12:13], 0, v[154:155]
	global_load_dwordx4 v[142:145], v[134:135], off
	s_nop 0
	global_load_dwordx4 v[134:137], v[134:135], off offset:16
	s_nop 0
	global_load_dwordx4 v[162:165], v[154:155], off
	s_nop 0
	global_load_dwordx4 v[154:157], v[154:155], off offset:16
	v_lshl_add_u64 v[152:153], v[152:153], 4, s[14:15]
	global_load_dwordx4 v[158:161], v[152:153], off
	v_lshlrev_b64 v[152:153], 5, v[150:151]
	v_lshl_add_u64 v[152:153], s[12:13], 0, v[152:153]
	global_load_dwordx4 v[192:195], v[152:153], off
	global_load_dwordx4 v[196:199], v[152:153], off offset:16
	v_lshl_add_u64 v[150:151], v[150:151], 4, s[14:15]
	global_load_dwordx4 v[200:203], v[150:151], off
	v_ashrrev_i32_e32 v149, 31, v148
	v_ashrrev_i32_e32 v147, 31, v146
	v_lshlrev_b64 v[150:151], 5, v[148:149]
	v_lshlrev_b64 v[152:153], 5, v[146:147]
	v_lshl_add_u64 v[148:149], v[148:149], 4, s[14:15]
	v_lshl_add_u64 v[216:217], v[146:147], 4, s[14:15]
	v_lshl_add_u64 v[146:147], s[12:13], 0, v[150:151]
	v_lshl_add_u64 v[150:151], s[12:13], 0, v[152:153]
	global_load_dwordx4 v[204:207], v[146:147], off
	global_load_dwordx4 v[208:211], v[146:147], off offset:16
	global_load_dwordx4 v[212:215], v[148:149], off
	s_nop 0
	global_load_dwordx4 v[146:149], v[150:151], off
	s_nop 0
	global_load_dwordx4 v[150:153], v[150:151], off offset:16
	s_waitcnt vmcnt(0)
	v_mov_b32_e32 v218, v139
	v_mov_b32_e32 v219, v140
	v_mov_b32_e32 v139, v141
	v_pk_add_f32 v[138:139], v[218:219], v[138:139]
	v_mov_b32_e32 v140, v142
	v_mov_b32_e32 v141, v134
	v_mov_b32_e32 v134, v143
	v_mov_b32_e32 v142, v144
	v_mov_b32_e32 v143, v136
	v_mov_b32_e32 v136, v145
	v_mov_b32_e32 v144, v162
	v_mov_b32_e32 v145, v154
	v_mov_b32_e32 v154, v163
	v_mov_b32_e32 v162, v164
	v_mov_b32_e32 v163, v156
	v_mov_b32_e32 v156, v165
	v_mov_b32_e32 v164, v159
	v_mov_b32_e32 v165, v160
	v_mov_b32_e32 v159, v161
	v_pk_add_f32 v[134:135], v[140:141], v[134:135]
	v_pk_add_f32 v[136:137], v[142:143], v[136:137]
	v_add_f32_e32 v2, v138, v139
	v_pk_add_f32 v[138:139], v[144:145], v[154:155]
	v_pk_add_f32 v[140:141], v[162:163], v[156:157]
	v_pk_add_f32 v[142:143], v[164:165], v[158:159]
	v_pk_add_f32 v[134:135], v[134:135], v[136:137]
	v_pk_add_f32 v[136:137], v[138:139], v[140:141]
	v_add_f32_e32 v5, v142, v143
	v_add_f32_e32 v134, v134, v135
	v_add_f32_e32 v135, v136, v137
	v_fmamk_f32 v2, v2, 0x3b000000, v189
	v_fmamk_f32 v5, v5, 0x3b000000, v189
	v_fmamk_f32 v134, v134, 0x3b000000, v189
	v_fmamk_f32 v135, v135, 0x3b000000, v189
	v_sqrt_f32_e32 v2, v2
	v_sqrt_f32_e32 v5, v5
	v_rsq_f32_e32 v136, v134
	v_rsq_f32_e32 v137, v135
	v_mov_b32_e32 v160, v192
	v_mov_b32_e32 v161, v196
	v_mov_b32_e32 v196, v193
	v_mov_b32_e32 v192, v194
	v_mov_b32_e32 v193, v198
	v_mov_b32_e32 v198, v195
	v_pk_add_f32 v[144:145], v[160:161], v[196:197]
	v_pk_add_f32 v[134:135], v[192:193], v[198:199]
	v_mul_f32_e32 v2, v136, v2
	v_pk_add_f32 v[138:139], v[144:145], v[134:135]
	v_mul_f32_e32 v140, v137, v5
	global_load_dwordx4 v[134:137], v[216:217], off
	v_pk_mul_f32 v[132:133], v[132:133], v[2:3] op_sel_hi:[1,0]
	v_pk_mul_f32 v[130:131], v[130:131], v[2:3] op_sel_hi:[1,0]
	v_pk_mul_f32 v[128:129], v[128:129], v[2:3] op_sel_hi:[1,0]
	v_pk_mul_f32 v[126:127], v[126:127], v[2:3] op_sel_hi:[1,0]
	v_pk_mul_f32 v[100:101], v[100:101], v[2:3] op_sel_hi:[1,0]
	v_pk_mul_f32 v[98:99], v[98:99], v[2:3] op_sel_hi:[1,0]
	v_pk_mul_f32 v[96:97], v[96:97], v[2:3] op_sel_hi:[1,0]
	v_pk_mul_f32 v[94:95], v[94:95], v[2:3] op_sel_hi:[1,0]
	v_add_f32_e32 v2, v138, v139
	v_mov_b32_e32 v138, v201
	v_mov_b32_e32 v139, v202
	v_mov_b32_e32 v201, v203
	v_add_u32_e32 v154, 0x90, v4
	v_pk_add_f32 v[138:139], v[138:139], v[200:201]
	v_ashrrev_i32_e32 v155, 31, v154
	v_add_f32_e32 v5, v138, v139
	v_lshlrev_b64 v[138:139], 5, v[154:155]
	v_lshl_add_u64 v[142:143], s[12:13], 0, v[138:139]
	v_pk_mul_f32 v[124:125], v[124:125], v[140:141] op_sel_hi:[1,0]
	v_pk_mul_f32 v[122:123], v[122:123], v[140:141] op_sel_hi:[1,0]
	v_pk_mul_f32 v[120:121], v[120:121], v[140:141] op_sel_hi:[1,0]
	v_pk_mul_f32 v[118:119], v[118:119], v[140:141] op_sel_hi:[1,0]
	v_pk_mul_f32 v[92:93], v[92:93], v[140:141] op_sel_hi:[1,0]
	v_pk_mul_f32 v[90:91], v[90:91], v[140:141] op_sel_hi:[1,0]
	v_pk_mul_f32 v[88:89], v[88:89], v[140:141] op_sel_hi:[1,0]
	v_pk_mul_f32 v[86:87], v[86:87], v[140:141] op_sel_hi:[1,0]
	global_load_dwordx4 v[138:141], v[142:143], off
	s_nop 0
	global_load_dwordx4 v[142:145], v[142:143], off offset:16
	v_fmamk_f32 v2, v2, 0x3b000000, v189
	v_fmamk_f32 v5, v5, 0x3b000000, v189
	v_lshl_add_u64 v[154:155], v[154:155], 4, s[14:15]
	v_rsq_f32_e32 v2, v2
	v_sqrt_f32_e32 v5, v5
	global_load_dwordx4 v[154:157], v[154:155], off
	v_mov_b32_e32 v158, v204
	v_mov_b32_e32 v159, v208
	v_mov_b32_e32 v208, v205
	v_mov_b32_e32 v160, v206
	v_mov_b32_e32 v161, v210
	v_mov_b32_e32 v210, v207
	v_pk_add_f32 v[158:159], v[158:159], v[208:209]
	v_pk_add_f32 v[160:161], v[160:161], v[210:211]
	v_mul_f32_e32 v2, v2, v5
	v_pk_add_f32 v[158:159], v[158:159], v[160:161]
	v_add_u32_e32 v192, 0xa0, v4
	v_add_f32_e32 v5, v158, v159
	v_mov_b32_e32 v158, v213
	v_mov_b32_e32 v159, v214
	v_mov_b32_e32 v213, v215
	v_pk_add_f32 v[158:159], v[158:159], v[212:213]
	v_ashrrev_i32_e32 v193, 31, v192
	v_add_f32_e32 v191, v158, v159
	v_lshlrev_b64 v[158:159], 5, v[192:193]
	v_lshl_add_u64 v[162:163], s[12:13], 0, v[158:159]
	global_load_dwordx4 v[158:161], v[162:163], off
; template <class Epi, class Sched, bool ALIGN_EPI = false, bool SP2 = false>
; __device__ __forceinline__ void gemm_phase(PG8_LAS unsigned char* lds, const Gemm g, const Sched& S, const Epi& E) {
;     ...
;         if constexpr (Epi::PAIR) { if (cur.half == 0) E.mid(acc, cur, wr, wc, fr, fq); else E(acc, cur, wr, wc, fr, fq); }
;         else if constexpr (!Epi::AFTER_DRAIN) { E(acc, cur, wr, wc, fr, fq); S.done(cur); }
;         if (!has_next) break;
;         if (!(Epi::PAIR && cur.half == 0))
;     __device__ __forceinline__ void mid(pg8::f32x4 (&acc)[2][2][4][2], const pg8::Unit& u, int wr, int wc, int fr, int fq) const {
;     ...
;                 const int r = row0 + ai * 128 + m * 16;
;                 const f32x4 a0 = *(const f32x4*)(SSA + (size_t)r * 8), a1 = *(const f32x4*)(SSA + (size_t)r * 8 + 4), m0 = *(const f32x4*)(SSM + (size_t)r * 4);
;                 const float ssa = ((a0[0] + a0[1]) + (a0[2] + a0[3])) + ((a1[0] + a1[1]) + (a1[2] + a1[3])), ssm = (m0[0] + m0[1]) + (m0[2] + m0[3]);
;                 const float ratio = __builtin_amdgcn_rsqf(ssa * (1.f / 512.f) + EPS) * __builtin_amdgcn_sqrtf(ssm * (1.f / 512.f) + EPS);
; #pragma unroll
;                 for (int bj = 0; bj < 2; ++bj) { acc[ai][bj][m][0] = acc[ai][bj][m][0] * ratio; acc[ai][bj][m][1] = acc[ai][bj][m][1] * ratio; }
;             }
;     }
	s_nop 0
	global_load_dwordx4 v[162:165], v[162:163], off offset:16
	v_lshl_add_u64 v[192:193], v[192:193], 4, s[14:15]
	v_fmamk_f32 v5, v5, 0x3b000000, v189
	v_fmamk_f32 v191, v191, 0x3b000000, v189
	global_load_dwordx4 v[192:195], v[192:193], off
	v_rsq_f32_e32 v5, v5
	v_sqrt_f32_e32 v191, v191
	v_add_u32_e32 v4, 0xb0, v4
	v_pk_mul_f32 v[116:117], v[116:117], v[2:3] op_sel_hi:[1,0]
	v_pk_mul_f32 v[114:115], v[114:115], v[2:3] op_sel_hi:[1,0]
	v_pk_mul_f32 v[112:113], v[112:113], v[2:3] op_sel_hi:[1,0]
	v_pk_mul_f32 v[110:111], v[110:111], v[2:3] op_sel_hi:[1,0]
	v_pk_mul_f32 v[84:85], v[84:85], v[2:3] op_sel_hi:[1,0]
	v_pk_mul_f32 v[82:83], v[82:83], v[2:3] op_sel_hi:[1,0]
	v_pk_mul_f32 v[80:81], v[80:81], v[2:3] op_sel_hi:[1,0]
	v_pk_mul_f32 v[78:79], v[78:79], v[2:3] op_sel_hi:[1,0]
	v_mul_f32_e32 v2, v5, v191
	v_mov_b32_e32 v196, v146
	v_mov_b32_e32 v197, v150
	v_mov_b32_e32 v150, v147
	v_mov_b32_e32 v146, v148
	v_mov_b32_e32 v147, v152
	v_mov_b32_e32 v152, v149
	v_ashrrev_i32_e32 v5, 31, v4
	v_pk_add_f32 v[198:199], v[146:147], v[152:153]
	v_lshlrev_b64 v[146:147], 5, v[4:5]
	v_pk_add_f32 v[196:197], v[196:197], v[150:151]
	v_lshl_add_u64 v[150:151], s[12:13], 0, v[146:147]
	global_load_dwordx4 v[146:149], v[150:151], off
	s_nop 0
	global_load_dwordx4 v[150:153], v[150:151], off offset:16
	v_pk_add_f32 v[196:197], v[196:197], v[198:199]
	v_lshl_add_u64 v[4:5], v[4:5], 4, s[14:15]
	v_add_f32_e32 v191, v196, v197
	s_waitcnt vmcnt(8)
	v_mov_b32_e32 v196, v135
	v_mov_b32_e32 v197, v136
	v_mov_b32_e32 v135, v137
	v_pk_add_f32 v[134:135], v[196:197], v[134:135]
	v_pk_mul_f32 v[108:109], v[108:109], v[2:3] op_sel_hi:[1,0]
	v_add_f32_e32 v196, v134, v135
	global_load_dwordx4 v[134:137], v[4:5], off
	v_fmamk_f32 v4, v191, 0x3b000000, v189
	v_fmamk_f32 v5, v196, 0x3b000000, v189
	v_rsq_f32_e32 v4, v4
	v_sqrt_f32_e32 v5, v5
	v_pk_mul_f32 v[106:107], v[106:107], v[2:3] op_sel_hi:[1,0]
	v_pk_mul_f32 v[104:105], v[104:105], v[2:3] op_sel_hi:[1,0]
	v_pk_mul_f32 v[102:103], v[102:103], v[2:3] op_sel_hi:[1,0]
	v_pk_mul_f32 v[76:77], v[76:77], v[2:3] op_sel_hi:[1,0]
	v_pk_mul_f32 v[74:75], v[74:75], v[2:3] op_sel_hi:[1,0]
	v_pk_mul_f32 v[72:73], v[72:73], v[2:3] op_sel_hi:[1,0]
	v_pk_mul_f32 v[70:71], v[70:71], v[2:3] op_sel_hi:[1,0]
	v_mul_f32_e32 v2, v4, v5
	v_pk_mul_f32 v[68:69], v[68:69], v[2:3] op_sel_hi:[1,0]
	s_waitcnt vmcnt(8)
	v_mov_b32_e32 v4, v138
	s_waitcnt vmcnt(7)
	v_mov_b32_e32 v5, v142
	v_mov_b32_e32 v142, v139
	v_mov_b32_e32 v138, v140
	v_mov_b32_e32 v139, v144
	v_mov_b32_e32 v144, v141
	v_pk_add_f32 v[4:5], v[4:5], v[142:143]
	v_pk_add_f32 v[138:139], v[138:139], v[144:145]
	v_pk_mul_f32 v[66:67], v[66:67], v[2:3] op_sel_hi:[1,0]
	v_pk_add_f32 v[4:5], v[4:5], v[138:139]
	v_pk_mul_f32 v[64:65], v[64:65], v[2:3] op_sel_hi:[1,0]
	v_add_f32_e32 v138, v4, v5
	s_waitcnt vmcnt(6)
	v_mov_b32_e32 v4, v155
	v_mov_b32_e32 v5, v156
	v_mov_b32_e32 v155, v157
	v_pk_add_f32 v[4:5], v[4:5], v[154:155]
	v_pk_mul_f32 v[62:63], v[62:63], v[2:3] op_sel_hi:[1,0]
	v_add_f32_e32 v4, v4, v5
	v_fmamk_f32 v5, v138, 0x3b000000, v189
	v_fmamk_f32 v4, v4, 0x3b000000, v189
	v_rsq_f32_e32 v5, v5
	v_sqrt_f32_e32 v4, v4
	v_pk_mul_f32 v[36:37], v[36:37], v[2:3] op_sel_hi:[1,0]
	v_pk_mul_f32 v[34:35], v[34:35], v[2:3] op_sel_hi:[1,0]
	v_pk_mul_f32 v[32:33], v[32:33], v[2:3] op_sel_hi:[1,0]
	v_pk_mul_f32 v[30:31], v[30:31], v[2:3] op_sel_hi:[1,0]
	v_mul_f32_e32 v2, v5, v4
	s_waitcnt vmcnt(5)
	v_mov_b32_e32 v4, v158
	s_waitcnt vmcnt(4)
	v_mov_b32_e32 v5, v162
	v_mov_b32_e32 v162, v159
	v_mov_b32_e32 v138, v160
	v_mov_b32_e32 v139, v164
	v_mov_b32_e32 v164, v161
	v_pk_add_f32 v[4:5], v[4:5], v[162:163]
	v_pk_add_f32 v[138:139], v[138:139], v[164:165]
	v_pk_mul_f32 v[60:61], v[60:61], v[2:3] op_sel_hi:[1,0]
	v_pk_add_f32 v[4:5], v[4:5], v[138:139]
	v_pk_mul_f32 v[58:59], v[58:59], v[2:3] op_sel_hi:[1,0]
	v_add_f32_e32 v138, v4, v5
	s_waitcnt vmcnt(3)
	v_mov_b32_e32 v4, v193
	v_mov_b32_e32 v5, v194
	v_mov_b32_e32 v193, v195
	v_pk_add_f32 v[4:5], v[4:5], v[192:193]
	v_pk_mul_f32 v[56:57], v[56:57], v[2:3] op_sel_hi:[1,0]
	v_add_f32_e32 v4, v4, v5
	v_fmamk_f32 v5, v138, 0x3b000000, v189
	v_fmamk_f32 v4, v4, 0x3b000000, v189
	v_rsq_f32_e32 v5, v5
	v_sqrt_f32_e32 v4, v4
	v_pk_mul_f32 v[54:55], v[54:55], v[2:3] op_sel_hi:[1,0]
	v_pk_mul_f32 v[28:29], v[28:29], v[2:3] op_sel_hi:[1,0]
	v_pk_mul_f32 v[26:27], v[26:27], v[2:3] op_sel_hi:[1,0]
	v_pk_mul_f32 v[24:25], v[24:25], v[2:3] op_sel_hi:[1,0]
	v_pk_mul_f32 v[22:23], v[22:23], v[2:3] op_sel_hi:[1,0]
	v_mul_f32_e32 v2, v5, v4
	s_waitcnt vmcnt(2)
	v_mov_b32_e32 v4, v146
	s_waitcnt vmcnt(1)
	v_mov_b32_e32 v5, v150
	v_mov_b32_e32 v150, v147
	v_mov_b32_e32 v138, v148
	v_mov_b32_e32 v139, v152
	v_mov_b32_e32 v152, v149
	v_pk_add_f32 v[4:5], v[4:5], v[150:151]
	v_pk_add_f32 v[138:139], v[138:139], v[152:153]
	v_pk_mul_f32 v[52:53], v[52:53], v[2:3] op_sel_hi:[1,0]
	v_pk_add_f32 v[4:5], v[4:5], v[138:139]
	v_pk_mul_f32 v[50:51], v[50:51], v[2:3] op_sel_hi:[1,0]
	v_add_f32_e32 v138, v4, v5
	s_waitcnt vmcnt(0)
	v_mov_b32_e32 v4, v135
	v_mov_b32_e32 v5, v136
	v_mov_b32_e32 v135, v137
	v_pk_add_f32 v[4:5], v[4:5], v[134:135]
	v_pk_mul_f32 v[48:49], v[48:49], v[2:3] op_sel_hi:[1,0]
	v_add_f32_e32 v4, v4, v5
	v_fmamk_f32 v5, v138, 0x3b000000, v189
	v_fmamk_f32 v4, v4, 0x3b000000, v189
	v_rsq_f32_e32 v5, v5
	v_sqrt_f32_e32 v4, v4
	v_pk_mul_f32 v[46:47], v[46:47], v[2:3] op_sel_hi:[1,0]
	v_pk_mul_f32 v[20:21], v[20:21], v[2:3] op_sel_hi:[1,0]
	v_pk_mul_f32 v[18:19], v[18:19], v[2:3] op_sel_hi:[1,0]
	v_pk_mul_f32 v[16:17], v[16:17], v[2:3] op_sel_hi:[1,0]
	v_pk_mul_f32 v[14:15], v[14:15], v[2:3] op_sel_hi:[1,0]
	v_mul_f32_e32 v2, v5, v4
	v_pk_mul_f32 v[44:45], v[44:45], v[2:3] op_sel_hi:[1,0]
	v_pk_mul_f32 v[42:43], v[42:43], v[2:3] op_sel_hi:[1,0]
	v_pk_mul_f32 v[40:41], v[40:41], v[2:3] op_sel_hi:[1,0]
	v_pk_mul_f32 v[38:39], v[38:39], v[2:3] op_sel_hi:[1,0]
	v_pk_mul_f32 v[12:13], v[12:13], v[2:3] op_sel_hi:[1,0]
	v_pk_mul_f32 v[10:11], v[10:11], v[2:3] op_sel_hi:[1,0]
	v_pk_mul_f32 v[8:9], v[8:9], v[2:3] op_sel_hi:[1,0]
	v_pk_mul_f32 v[6:7], v[6:7], v[2:3] op_sel_hi:[1,0]
	s_branch .Lpin_7
	.p2align 8
	s_nop 0
	s_nop 0
	s_nop 0
	s_nop 0
	s_nop 0
	s_nop 0
	s_nop 0
	s_nop 0
	s_nop 0
	s_nop 0
	s_nop 0
	s_nop 0
	s_nop 0
	s_nop 0
	s_nop 0
	s_nop 0
	s_nop 0
	s_nop 0
	s_nop 0
; template <class Epi, class Sched, bool ALIGN_EPI = false, bool SP2 = false>
; __device__ __forceinline__ void gemm_phase(PG8_LAS unsigned char* lds, const Gemm g, const Sched& S, const Epi& E) {
;     ...
;         if constexpr (Epi::PAIR) { if (cur.half == 0) E.mid(acc, cur, wr, wc, fr, fq); else E(acc, cur, wr, wc, fr, fq); }
;         else if constexpr (!Epi::AFTER_DRAIN) { E(acc, cur, wr, wc, fr, fq); S.done(cur); }
;         if (!has_next) break;
;         if (!(Epi::PAIR && cur.half == 0))
; #pragma unroll
;         for (int a = 0; a < 2; ++a)
; #pragma unroll
;             for (int b = 0; b < 2; ++b)
; #pragma unroll
;                 for (int m = 0; m < 4; ++m)
; #pragma unroll
;                     for (int n = 0; n < 2; ++n) acc[a][b][m][n] = (f32x4){0.f, 0.f, 0.f, 0.f};
;         cur = nxt; cA = nA; cB = nB; ++ui;
.Lpin_7:
.LBB0_1157:
	s_andn2_b64 vcc, exec, s[0:1]
	s_mov_b64 s[0:1], -1
	s_cbranch_vccnz .LBB0_1139
	s_andn2_b64 vcc, exec, s[36:37]
	s_cbranch_vccnz .LBB0_1160
	v_mov_b32_e32 v4, v3
	v_mov_b32_e32 v5, v3
	v_mov_b32_e32 v2, v3
	v_mov_b64_e32 v[8:9], v[4:5]
	v_mov_b64_e32 v[12:13], v[4:5]
	v_mov_b64_e32 v[16:17], v[4:5]
	v_mov_b64_e32 v[20:21], v[4:5]
	v_mov_b64_e32 v[24:25], v[4:5]
	v_mov_b64_e32 v[28:29], v[4:5]
	v_mov_b64_e32 v[32:33], v[4:5]
	v_mov_b64_e32 v[36:37], v[4:5]
	v_mov_b64_e32 v[40:41], v[4:5]
	v_mov_b64_e32 v[44:45], v[4:5]
	v_mov_b64_e32 v[48:49], v[4:5]
	v_mov_b64_e32 v[52:53], v[4:5]
	v_mov_b64_e32 v[56:57], v[4:5]
	v_mov_b64_e32 v[60:61], v[4:5]
	v_mov_b64_e32 v[64:65], v[4:5]
	v_mov_b64_e32 v[68:69], v[4:5]
	v_mov_b64_e32 v[72:73], v[4:5]
	v_mov_b64_e32 v[76:77], v[4:5]
	v_mov_b64_e32 v[80:81], v[4:5]
	v_mov_b64_e32 v[84:85], v[4:5]
	v_mov_b64_e32 v[88:89], v[4:5]
	v_mov_b64_e32 v[92:93], v[4:5]
	v_mov_b64_e32 v[96:97], v[4:5]
	v_mov_b64_e32 v[100:101], v[4:5]
	v_mov_b64_e32 v[104:105], v[4:5]
	v_mov_b64_e32 v[108:109], v[4:5]
	v_mov_b64_e32 v[112:113], v[4:5]
	v_mov_b64_e32 v[116:117], v[4:5]
	v_mov_b64_e32 v[120:121], v[4:5]
	v_mov_b64_e32 v[124:125], v[4:5]
	v_mov_b64_e32 v[128:129], v[4:5]
	v_mov_b64_e32 v[132:133], v[4:5]
	v_mov_b64_e32 v[6:7], v[2:3]
	v_mov_b64_e32 v[10:11], v[2:3]
	v_mov_b64_e32 v[14:15], v[2:3]
	v_mov_b64_e32 v[18:19], v[2:3]
	v_mov_b64_e32 v[22:23], v[2:3]
	v_mov_b64_e32 v[26:27], v[2:3]
	v_mov_b64_e32 v[30:31], v[2:3]
	v_mov_b64_e32 v[34:35], v[2:3]
	v_mov_b64_e32 v[38:39], v[2:3]
	v_mov_b64_e32 v[42:43], v[2:3]
	v_mov_b64_e32 v[46:47], v[2:3]
	v_mov_b64_e32 v[50:51], v[2:3]
	v_mov_b64_e32 v[54:55], v[2:3]
	v_mov_b64_e32 v[58:59], v[2:3]
	v_mov_b64_e32 v[62:63], v[2:3]
	v_mov_b64_e32 v[66:67], v[2:3]
	v_mov_b64_e32 v[70:71], v[2:3]
	v_mov_b64_e32 v[74:75], v[2:3]
	v_mov_b64_e32 v[78:79], v[2:3]
	v_mov_b64_e32 v[82:83], v[2:3]
	v_mov_b64_e32 v[86:87], v[2:3]
	v_mov_b64_e32 v[90:91], v[2:3]
	v_mov_b64_e32 v[94:95], v[2:3]
	v_mov_b64_e32 v[98:99], v[2:3]
	v_mov_b64_e32 v[102:103], v[2:3]
	v_mov_b64_e32 v[106:107], v[2:3]
	v_mov_b64_e32 v[110:111], v[2:3]
	v_mov_b64_e32 v[114:115], v[2:3]
	v_mov_b64_e32 v[118:119], v[2:3]
	v_mov_b64_e32 v[122:123], v[2:3]
	v_mov_b64_e32 v[126:127], v[2:3]
	v_mov_b64_e32 v[130:131], v[2:3]

; template <bool FIRST>
; __device__ __forceinline__ void phase_norm(const Args& a, LAS unsigned char* lds, int tid, int wave, int lane, int vcu, int G) {
;     ...
;     const int sh_off = FIRST ? 0 : 3072, sc_off = FIRST ? 1024 : 4096;
;     const int gw = vcu * NWAVES + wave, NGW = G * NWAVES;
;     const int nit = G == 256 ? 5 : (MT + 2 * NGW - 1) / (2 * NGW);
.LBB0_1258:
	s_or_b64 exec, exec, s[2:3]
	s_waitcnt lgkmcnt(0)
	s_barrier
	s_branch .Lpin_8
	.p2align 8
	s_nop 0
	s_nop 0
	s_nop 0
	s_nop 0
	s_nop 0
	s_nop 0
	s_nop 0
	s_nop 0
	s_nop 0
	s_nop 0
	s_nop 0
.Lpin_8:
.LBB0_1259:
	s_cmp_lt_i32 s86, 8
	s_cselect_b64 s[4:5], -1, 0
	s_and_b64 s[0:1], s[4:5], s[0:1]
	s_andn2_b64 vcc, exec, s[0:1]
	s_cbranch_vccnz .LBB0_1281
	v_readlane_b32 s0, v253, 2
	s_cmpk_lg_i32 s0, 0x100
	s_cselect_b64 s[6:7], -1, 0
	s_cmpk_eq_i32 s0, 0x100
	s_mov_b32 s20, 5
	v_readlane_b32 s1, v253, 3
	s_cbranch_scc1 .LBB0_1262
	v_readlane_b32 s0, v253, 2
	v_readlane_b32 s1, v253, 3
	s_lshl_b32 s0, s0, 4
	s_abs_i32 s1, s0
	s_waitcnt vmcnt(0)
	v_cvt_f32_u32_e32 v2, s1
	s_sub_i32 s3, 0, s1
	s_add_i32 s2, s0, 0x43ff
	s_xor_b32 s0, s2, s0
	v_rcp_iflag_f32_e32 v2, v2
	s_abs_i32 s2, s2
	s_ashr_i32 s0, s0, 31
	v_mul_f32_e32 v2, 0x4f7ffffe, v2
	v_cvt_u32_f32_e32 v2, v2
	s_nop 0
	v_readfirstlane_b32 s8, v2
	s_mul_i32 s3, s3, s8
	s_mul_hi_u32 s3, s8, s3
	s_add_i32 s8, s8, s3
	s_mul_hi_u32 s3, s2, s8
	s_mul_i32 s8, s3, s1
	s_sub_i32 s2, s2, s8
	s_add_i32 s9, s3, 1
	s_sub_i32 s8, s2, s1
	s_cmp_ge_u32 s2, s1
	s_cselect_b32 s3, s9, s3
	s_cselect_b32 s2, s8, s2
	s_add_i32 s8, s3, 1
	s_cmp_ge_u32 s2, s1
	s_cselect_b32 s1, s8, s3
	s_xor_b32 s1, s1, s0
	s_sub_i32 s20, s1, s0

; #define PG8_BAR __builtin_amdgcn_s_barrier()
; template <class Epi, class Sched, bool ALIGN_EPI = false, bool SP2 = false>
; __device__ __forceinline__ void gemm_phase(PG8_LAS unsigned char* lds, const Gemm g, const Sched& S, const Epi& E) {
;     const int tid = threadIdx.x, wid = __builtin_amdgcn_readfirstlane(tid >> 6), lane = tid & 63, wr = wid >> 2, wc = wid & 3, fr = lane & 15, fq = lane >> 4;
;     const int K = g.K, nt = K / BK;
;     unsigned voffA[2], voffB[2];
; #pragma unroll
;     for (int i = 0; i < 2; ++i) { int R, C; stage_rc(tid * 16 + i * 8192, R, C); const int Rb = Epi::PERM ? ((R & ~31) + perm32(R & 31)) : R;
;         voffA[i] = (unsigned)(R * K + C) * 2u; voffB[i] = (unsigned)(Rb * K + C) * 2u; }
;     const size_t kstep = (size_t)(BK * 2);
;     const size_t hstep = (size_t)HALF * K * 2;
;     const size_t tstep = 2 * hstep;
;     const unsigned ldsw = (unsigned)wid * 1024u;
;     const int aoff = lds_byte(wr * 64 + fr, fq * 8), boff = lds_byte(wc * 32 + fr, fq * 8);
;     ...
;     Unit cur, nxt; int ui = 0;
;     if (!S.next(0, cur)) return;
;     f32x4 acc[2][2][4][2];
; #pragma unroll
;     for (int a = 0; a < 2; ++a)
; #pragma unroll
;         for (int b = 0; b < 2; ++b)
; #pragma unroll
;             for (int m = 0; m < 4; ++m)
; #pragma unroll
;                 for (int n = 0; n < 2; ++n) acc[a][b][m][n] = (f32x4){0.f, 0.f, 0.f, 0.f};
;     bf16x8 At[4][2], B0[2][2], B1[2][2];
;     const char* cA; const char* cB;
;     if constexpr (Epi::PAIR) { cA = (const char*)(cur.half ? g.A2 : g.A) + (size_t)cur.pm * tstep; cB = (const char*)(cur.half ? g.Bt2 : g.Bt) + (size_t)cur.pn * tstep; }
;     else { cA = (const char*)g.A + (size_t)cur.pm * tstep; cB = (const char*)g.Bt + (size_t)cur.pn * tstep; }
;     S.a_ready(cur);
;     if constexpr (SP2) {
;         PG8_STAGE(PG8_SB(0, 0), cB, voffB); PG8_STAGE(PG8_SB(0, 1), cB + hstep, voffB); PG8_STAGE(PG8_SA(0, 0), cA, voffA); PG8_STAGE(PG8_SA(0, 1), cA + hstep, voffA);
;         if (wr == 1) PG8_BAR;
;         PG8_WAIT_V(2); PG8_BAR;
;         PG8_STAGE(PG8_SB(1, 0), cB + kstep, voffB); PG8_STAGE(PG8_SA(1, 0), cA + kstep, voffA); PG8_STAGE(PG8_SB(1, 1), cB + hstep + kstep, voffB);
;         PG8_WAIT_V(6); PG8_BAR;
;     } else {
;         PG8_STAGE(PG8_SB(0, 0), cB, voffB); PG8_STAGE(PG8_SA(0, 0), cA, voffA); PG8_STAGE(PG8_SB(0, 1), cB + hstep, voffB); PG8_STAGE(PG8_SA(0, 1), cA + hstep, voffA);
.LBB0_1330:
	s_or_b64 exec, exec, s[2:3]
	s_waitcnt lgkmcnt(0)
	s_barrier
	s_branch .Lpin_9
	.p2align 8
	s_nop 0
	s_nop 0
	s_nop 0
	s_nop 0
	s_nop 0
	s_nop 0
	s_nop 0
	s_nop 0
	s_nop 0
	s_nop 0
	s_nop 0
	s_nop 0
	s_nop 0
	s_nop 0
	s_nop 0
	s_nop 0
	s_nop 0
	s_nop 0
	s_nop 0
	s_nop 0
	s_nop 0
	s_nop 0
	s_nop 0
	s_nop 0
	s_nop 0
	s_nop 0
	s_nop 0
	s_nop 0
	s_nop 0
	s_nop 0
	s_nop 0
	s_nop 0
	s_nop 0
	s_nop 0
	s_nop 0
	s_nop 0
	s_nop 0
.Lpin_9:
.LBB0_1331:
	s_cmp_lt_i32 s86, 9
	s_cselect_b64 s[2:3], -1, 0
	s_and_b64 s[0:1], s[2:3], s[0:1]
	s_andn2_b64 vcc, exec, s[0:1]
	s_cbranch_vccnz .LBB0_1361
	s_add_u32 s6, s84, 0x5b00000
	s_addc_u32 s7, s85, 0
	s_add_u32 s8, s84, 0x1600000
	s_addc_u32 s9, s85, 0
	s_add_u32 s4, s84, 0x19e00000
	s_addc_u32 s5, s85, 0
	v_readlane_b32 s11, v253, 4
	v_and_b32_e32 v148, 15, v0
	s_cmpk_gt_i32 s11, 0x1ff
	v_readfirstlane_b32 s1, v0
	s_cbranch_scc1 .LBB0_1352
	s_waitcnt vmcnt(0)
	v_lshlrev_b32_e32 v3, 1, v168
	v_lshrrev_b32_e32 v4, 5, v0
	v_and_b32_e32 v2, 32, v0
	v_and_b32_e32 v3, 24, v3
	v_and_b32_e32 v4, 4, v4
	v_and_b32_e32 v5, 3, v168
	v_and_b32_e32 v12, 15, v168
	v_bitop3_b32 v10, v1, v2, 48 bitop3:0x6c
	v_and_b32_e32 v11, 64, v0
	v_or3_b32 v3, v4, v5, v3
	v_lshrrev_b32_e32 v4, 3, v0
	v_or_b32_e32 v2, v10, v11
	v_and_or_b32 v5, v4, 48, v12
	v_and_or_b32 v4, v4, 32, v3
	v_or_b32_e32 v13, 0x2000, v1
	v_lshl_or_b32 v132, v4, 11, v2
	v_lshrrev_b32_e32 v4, 7, v13
	s_movk_i32 s0, 0x70
	v_lshl_or_b32 v130, v5, 11, v2
	v_and_or_b32 v5, v4, s0, v12
	s_movk_i32 s0, 0x60
	s_ashr_i32 s42, s11, 31
	v_and_or_b32 v3, v4, s0, v3
	s_lshr_b32 s0, s42, 29
	s_add_i32 s0, s11, s0
	s_ashr_i32 s10, s0, 3
	s_and_b32 s0, s0, -8
	s_lshr_b32 s12, s1, 6
	s_sub_i32 s0, s11, s0
	s_lshr_b32 s14, s1, 8
	s_lshl_b32 s33, s12, 10
	s_lshl_b32 s13, s0, 6
	s_mul_i32 s11, s0, 0x41
	s_cmp_lt_i32 s0, 0
	s_cselect_b32 s0, s11, s13
	s_add_i32 s0, s0, s10
	s_ashr_i32 s10, s0, 31
	s_lshr_b32 s10, s10, 26
	s_add_i32 s10, s0, s10
	s_ashr_i32 s11, s10, 6
	s_and_b32 s10, s10, 0xffc0
	s_sub_i32 s10, s0, s10
	s_bfe_i32 s0, s10, 0x80000
	s_bfe_u32 s0, s0, 0x3000c
	s_add_i32 s13, s10, s0
	s_bfe_i32 s0, s13, 0x80000
	s_and_b32 s13, s13, 0xf8
	s_sub_i32 s10, s10, s13
	s_lshl_b32 s11, s11, 3
	s_sext_i32_i16 s0, s0
	s_sext_i32_i8 s10, s10
	s_lshr_b32 s0, s0, 3
	s_add_i32 s34, s11, s10
	s_ashr_i32 s35, s34, 31
	s_bfe_i64 s[16:17], s[0:1], 0x100000
	s_lshl_b64 s[10:11], s[34:35], 19
	s_lshl_b64 s[16:17], s[16:17], 19
	s_add_u32 s38, s8, s16
	s_addc_u32 s39, s9, s17
	s_add_i32 s35, s33, 0
	s_add_i32 m0, s35, 0x10000
	v_lshl_or_b32 v136, v3, 11, v2
	global_load_lds_dwordx4 v132, s[38:39]
	s_add_i32 m0, s35, 0x12000
	s_add_u32 s16, s38, 0x40000
	global_load_lds_dwordx4 v136, s[38:39]
	s_addc_u32 s17, s39, 0
	s_add_i32 m0, s35, 0x14000
	v_lshl_or_b32 v134, v5, 11, v2
	global_load_lds_dwordx4 v132, s[16:17]
	s_add_i32 m0, s35, 0x16000
	s_add_u32 s36, s6, s10
	s_addc_u32 s37, s7, s11
	s_add_i32 s43, s35, 0x2000
	global_load_lds_dwordx4 v136, s[16:17]
	s_mov_b32 m0, s35
	s_add_u32 s10, s36, 0x40000
	global_load_lds_dwordx4 v130, s[36:37]
	s_mov_b32 m0, s43
	s_addc_u32 s11, s37, 0
	s_add_i32 s44, s35, 0x4000
	global_load_lds_dwordx4 v134, s[36:37]
	s_mov_b32 m0, s44
	s_add_i32 s45, s35, 0x6000
	global_load_lds_dwordx4 v130, s[10:11]
	s_mov_b32 m0, s45
	v_mov_b32_e32 v133, 0
	global_load_lds_dwordx4 v134, s[10:11]
	v_mov_b32_e32 v137, v133
	v_mov_b32_e32 v131, v133
	v_mov_b32_e32 v135, v133
	s_cmp_eq_u32 s14, 1
	s_mov_b32 s46, 0
	v_lshl_add_u64 v[8:9], s[38:39], 0, v[132:133]
	v_lshl_add_u64 v[6:7], s[38:39], 0, v[136:137]
	v_lshl_add_u64 v[2:3], s[36:37], 0, v[130:131]
	s_cselect_b64 s[10:11], -1, 0
	s_cmp_lg_u32 s14, 1
	v_lshl_add_u64 v[4:5], s[36:37], 0, v[134:135]
	s_cbranch_scc1 .LBB0_1335
	s_barrier

; #define LAS __attribute__((address_space(3)))
; __device__ __forceinline__ void phase9(const Args& a, LAS unsigned char* lds, int tid, int wave, int lane, int vcu, int G) {
;     unsigned char* ws = a.ws;
;     const bf16* KEYS = (const bf16*)(ws + WS_KEYS); const bf16* QP = (const bf16*)(ws + WS_QP); const bf16* U16 = (const bf16*)(ws + WS_U); const bf16* V16 = (const bf16*)(ws + WS_V);
;     const float* X1 = (const float*)(ws + WS_X1); const float* mod = (const float*)(ws + WS_MOD);
;     int* SEL_E = (int*)(ws + WS_SELE); float* SEL_G = (float*)(ws + WS_SELG);
;     const int i16 = lane & 15, g = lane >> 4;
;     LAS unsigned char* KL = lds + 16384;
;     int hprev = -1;
;     for (int u = vcu; u < 8 * (MT / 128); u += G) {
.Lpin_10:
.LBB0_1411:
	s_cmp_lt_i32 s86, 10
	s_cselect_b64 s[18:19], -1, 0
	s_and_b64 s[0:1], s[18:19], s[0:1]
	s_andn2_b64 vcc, exec, s[0:1]
	s_cbranch_vccnz .LBB0_1606
	v_readlane_b32 s0, v253, 5
	s_cmpk_gt_i32 s0, 0x43f
	v_readlane_b32 s1, v253, 6
	s_cbranch_scc1 .LBB0_1581
	s_waitcnt vmcnt(0)
	v_and_b32_e32 v3, 15, v0
	v_readlane_b32 s0, v253, 27
	v_mul_u32_u24_e32 v4, 0x110, v3
	v_and_b32_e32 v5, 48, v0
	v_lshl_or_b32 v34, s0, 4, v3
	v_mov_b32_e32 v37, 0
	v_add3_u32 v42, 0, v4, v5
	v_lshlrev_b32_e32 v4, 4, v3
	v_mbcnt_lo_u32_b32 v3, -1, 0
	v_mov_b32_e32 v5, v37
	v_mbcnt_hi_u32_b32 v3, -1, v3
	v_lshl_add_u64 v[6:7], s[84:85], 0, v[4:5]
	s_mov_b64 s[4:5], 0x1a00000
	v_and_b32_e32 v5, 64, v3
	v_lshl_add_u64 v[38:39], v[6:7], 0, s[4:5]
	v_add_u32_e32 v5, 64, v5
	v_xor_b32_e32 v6, 16, v3
	v_or_b32_e32 v7, 0xa00, v0
	v_cmp_lt_i32_e32 vcc, v6, v5
	v_lshrrev_b32_e32 v8, 4, v7
	v_lshlrev_b32_e32 v84, 7, v8
	v_cndmask_b32_e32 v6, v3, v6, vcc
	v_or_b32_e32 v8, 0xc00, v0
	s_movk_i32 s4, 0xe00
	s_add_u32 s20, s84, 0x19e00000
	v_lshlrev_b32_e32 v77, 2, v6
	v_xor_b32_e32 v6, 32, v3
	v_lshrrev_b32_e32 v9, 4, v8
	v_cmp_gt_u32_e64 s[4:5], s4, v8
	v_or_b32_e32 v8, 0xe00, v0
	s_addc_u32 s21, s85, 0
	v_cmp_lt_i32_e32 vcc, v6, v5
	v_lshrrev_b32_e32 v10, 4, v8
	s_add_u32 s22, s84, 0x21400000
	v_cndmask_b32_e32 v3, v3, v6, vcc
	v_or_b32_e32 v5, 0x200, v0
	v_or_b32_e32 v6, 0x600, v0
	v_lshlrev_b32_e32 v86, 7, v10
	v_mov_b32_e32 v10, 0x8800
	s_addc_u32 s23, s85, 0
	v_lshrrev_b32_e32 v1, 4, v166
	s_movk_i32 s6, 0x110
	v_lshlrev_b32_e32 v78, 2, v3
	v_lshrrev_b32_e32 v3, 4, v0
	v_lshrrev_b32_e32 v5, 4, v5
	v_lshrrev_b32_e32 v6, 4, v6
	v_bfe_u32 v7, v7, 4, 6
	v_lshlrev_b32_e32 v85, 7, v9
	v_and_b32_e32 v9, 0x5f, v9
	v_mad_u32_u24 v10, 1, v10, 0
	v_bfe_u32 v8, v8, 4, 7
	s_add_u32 s24, s84, 0x21d00000
	v_readlane_b32 s1, v253, 28
	v_lshlrev_b32_e32 v2, 3, v1
	v_lshlrev_b32_e32 v43, 2, v1
	v_lshlrev_b32_e32 v79, 7, v3
	v_mad_u32_u24 v3, v3, s6, 0
	v_lshlrev_b32_e32 v80, 7, v5
	v_mad_u32_u24 v5, v5, s6, 0
	v_lshlrev_b32_e32 v82, 7, v6
	v_mad_u32_u24 v6, v6, s6, 0
	v_mad_u32_u24 v7, v7, s6, 0
	v_mad_u32_u24 v9, v9, s6, 0
	v_mad_u32_u24 v8, v8, s6, v10
	v_readlane_b32 s8, v253, 5
	s_addc_u32 s25, s85, 0
	v_mov_b32_e32 v35, v37
	s_mov_b32 s27, 0
	v_or_b32_e32 v44, 64, v43
	v_or_b32_e32 v45, 16, v43
	s_movk_i32 s33, 0x50
	v_or_b32_e32 v46, 0x50, v43
	v_or_b32_e32 v47, 32, v43
	s_movk_i32 s36, 0x60
	v_or_b32_e32 v48, 0x60, v43
	v_or_b32_e32 v49, 48, v43
	s_movk_i32 s37, 0x70
	v_or_b32_e32 v50, 0x70, v43
	v_add_u32_e32 v51, 0xc800, v42
	v_cmp_gt_u32_e64 s[0:1], 16, v166
	v_cmp_lt_u32_e64 s[2:3], 15, v166
	v_lshl_add_u32 v52, v0, 5, 0
	v_or_b32_e32 v53, 1, v43
	s_movk_i32 s38, 0x41
	v_or_b32_e32 v54, 0x41, v43
	v_or_b32_e32 v55, 2, v43
	s_movk_i32 s39, 0x42
	v_or_b32_e32 v56, 0x42, v43
	v_or_b32_e32 v57, 3, v43
	v_or_b32_e32 v58, 0x43, v43
	v_or_b32_e32 v59, 17, v43
	s_movk_i32 s40, 0x51
	v_or_b32_e32 v60, 0x51, v43
	v_or_b32_e32 v61, 18, v43
	v_or_b32_e32 v62, 0x52, v43
	v_or_b32_e32 v63, 19, v43
	v_or_b32_e32 v64, 0x53, v43
	v_or_b32_e32 v65, 33, v43
	s_movk_i32 s41, 0x61
	v_or_b32_e32 v66, 0x61, v43
	v_or_b32_e32 v67, 34, v43
	v_or_b32_e32 v68, 0x62, v43
	v_or_b32_e32 v69, 35, v43
	v_or_b32_e32 v70, 0x63, v43
	v_or_b32_e32 v71, 49, v43
	s_movk_i32 s42, 0x71
	v_or_b32_e32 v72, 0x71, v43
	v_or_b32_e32 v73, 50, v43
	v_or_b32_e32 v74, 0x72, v43
	v_or_b32_e32 v75, 51, v43
	v_or_b32_e32 v76, 0x73, v43
	s_mov_b32 s55, -1
	v_or_b32_e32 v81, 0x2000, v79
	v_or_b32_e32 v83, 0x4000, v79
	v_lshlrev_b32_e32 v36, 1, v2
	v_add_u32_e32 v87, v3, v4
	v_add_u32_e32 v88, v5, v4
	v_add_u32_e32 v89, v6, v4
	v_add_u32_e32 v90, v7, v4
	v_add_u32_e32 v91, v9, v4
	v_add_u32_e32 v92, v8, v4
	s_brev_b32 s43, -2
	s_mov_b32 s44, 0x7fffff00
	v_cmp_ne_u32_e64 s[6:7], 1, v1
	s_movk_i32 s45, 0xe0
	s_movk_i32 s46, 0xf0
	s_movk_i32 s47, 0x80
	s_movk_i32 s48, 0x90
	s_movk_i32 s49, 0xa0
	s_movk_i32 s50, 0xb0
	s_movk_i32 s51, 0xc0
	s_movk_i32 s52, 0xd0
	s_movk_i32 s53, 0x7f00
	v_mov_b32_e32 v93, 0x7fffff00
	s_mov_b32 s54, s8
	v_readlane_b32 s9, v253, 6
	s_branch .LBB0_1415

; __device__ __forceinline__ void phase10(const Args& a, LAS unsigned char* lds, int tid, int wave, int lane, int vcu, int G, int emask, bool probe) {
;     ...
;     const int nrounds = G == 256 ? 3 : (MT + GTK * NGW - 1) / (GTK * NGW);
.LBB0_1655:
	s_or_b64 exec, exec, s[2:3]
	s_waitcnt lgkmcnt(0)
	s_barrier
	s_branch .Lpin_11
	.p2align 8
	s_nop 0
	s_nop 0
	s_nop 0
	s_nop 0
	s_nop 0
	s_nop 0
	s_nop 0
	s_nop 0
	s_nop 0
	s_nop 0
	s_nop 0
	s_nop 0
	s_nop 0
	s_nop 0
	s_nop 0
	s_nop 0
	s_nop 0
	s_nop 0
	s_nop 0
	s_nop 0
	s_nop 0
	s_nop 0
	s_nop 0
.Lpin_11:
.LBB0_1656:
	s_cmp_gt_i32 s86, 10
	s_cselect_b64 s[2:3], -1, 0
	s_xor_b64 s[0:1], s[0:1], -1
	s_or_b64 s[0:1], s[2:3], s[0:1]
	s_and_b64 vcc, exec, s[0:1]
	s_cbranch_vccnz .LBB0_1777
	v_readlane_b32 s0, v253, 2
	s_cmpk_lg_i32 s0, 0x100
	s_cselect_b64 s[12:13], -1, 0
	s_cmpk_eq_i32 s0, 0x100
	s_mov_b32 s33, 3
	v_readlane_b32 s1, v253, 3
	s_cbranch_scc1 .LBB0_1659
	v_readlane_b32 s0, v253, 2
	v_readlane_b32 s1, v253, 3
	s_mul_i32 s0, s0, 24
	s_abs_i32 s1, s0
	v_cvt_f32_u32_e32 v1, s1
	s_sub_i32 s3, 0, s1
	s_add_i32 s2, s0, 0x43ff
	s_xor_b32 s0, s2, s0
	v_rcp_iflag_f32_e32 v1, v1
	s_abs_i32 s2, s2
	s_ashr_i32 s0, s0, 31
	v_mul_f32_e32 v1, 0x4f7ffffe, v1
	v_cvt_u32_f32_e32 v1, v1
	s_nop 0
	v_readfirstlane_b32 s4, v1
	s_mul_i32 s3, s3, s4
	s_mul_hi_u32 s3, s4, s3
	s_add_i32 s4, s4, s3
	s_mul_hi_u32 s3, s2, s4
	s_mul_i32 s4, s3, s1
	s_sub_i32 s2, s2, s4
	s_add_i32 s5, s3, 1
	s_sub_i32 s4, s2, s1
	s_cmp_ge_u32 s2, s1
	s_cselect_b32 s3, s5, s3
	s_cselect_b32 s2, s4, s2
	s_add_i32 s4, s3, 1
	s_cmp_ge_u32 s2, s1
	s_cselect_b32 s1, s4, s3
	s_xor_b32 s1, s1, s0
	s_sub_i32 s33, s1, s0
